# FFN-F2 epilogue cache-warming loads with six distinct destination registers
# speedup vs baseline: 1.0041x; 1.0041x over previous
.LBB0_1060:
	s_lshl_b32 s0, s3, 8
	s_add_i32 s0, s0, s60
	s_cmpk_lt_i32 s0, 0x2000
	s_movk_i32 s20, 0xfff
	v_lshl_or_b32 v192, s2, 8, v223
	s_cselect_b32 s14, s20, 0x7ff
	s_or_b32 s2, s0, 63
	s_and_b32 s1, s14, s0
	s_and_b32 s15, s14, s2
	v_or_b32_e32 v226, s0, v221
	v_mov_b64_e32 v[208:209], s[10:11]
	s_movk_i32 s26, 0x2c00
	v_ashrrev_i32_e32 v193, 31, v192
	v_mad_i64_i32 v[152:153], s[2:3], v226, s26, v[208:209]
	s_cmp_eq_u32 s1, 0
	s_mul_i32 s1, s0, 0x2c00
	v_lshlrev_b64 v[204:205], 1, v[192:193]
	s_cselect_b64 s[62:63], -1, 0
	s_mul_hi_i32 s3, s0, 0x2c00
	s_add_u32 s2, s10, s1
	v_lshl_add_u64 v[194:195], v[152:153], 0, v[204:205]
	s_mov_b32 s21, 0x2c000
	s_addc_u32 s3, s11, s3
	v_add_co_u32_e32 v198, vcc, s21, v194
	s_and_b64 s[12:13], s[62:63], exec
	s_nop 0
	v_addc_co_u32_e32 v199, vcc, 0, v195, vcc
	s_mov_b32 s22, 0x58000
	s_cselect_b32 s12, 0, 0xffffd400
	s_cselect_b32 s13, 0, -1
	s_cmp_eq_u32 s15, s14
	v_add_co_u32_e32 v200, vcc, s22, v194
	s_cselect_b64 s[50:51], -1, 0
	v_lshlrev_b64 v[88:89], 2, v[192:193]
	v_addc_co_u32_e32 v201, vcc, 0, v195, vcc
	s_mov_b32 s23, 0x84000
	v_lshl_add_u64 v[202:203], s[2:3], 0, v[204:205]
	s_and_b64 s[2:3], s[50:51], exec
	v_lshl_add_u64 v[190:191], s[18:19], 0, v[88:89]
	v_lshl_add_u64 v[90:91], s[46:47], 0, v[88:89]
	v_lshl_add_u64 v[96:97], s[48:49], 0, v[88:89]
	v_add_co_u32_e32 v206, vcc, s23, v194
	s_cselect_b32 s72, 0, 0xb0000
	v_lshl_add_u64 v[188:189], s[30:31], 0, v[88:89]
	global_load_dwordx4 v[100:103], v[190:191], off offset:16
	global_load_dwordx4 v[120:123], v[190:191], off
	global_load_dwordx4 v[92:95], v[90:91], off offset:16
	global_load_dwordx4 v[112:115], v[90:91], off
	s_nop 0
	global_load_dwordx4 v[88:91], v[96:97], off offset:16
	global_load_dwordx4 v[108:111], v[96:97], off
	s_nop 0
	global_load_dwordx4 v[96:99], v[188:189], off offset:16
	global_load_dwordx4 v[116:119], v[188:189], off
	global_load_dwordx4 v[172:175], v[194:195], off
	v_addc_co_u32_e32 v207, vcc, 0, v195, vcc
	v_lshl_add_u64 v[196:197], v[202:203], 0, s[12:13]
	v_lshl_add_u64 v[202:203], v[202:203], 0, s[72:73]
	global_load_dwordx4 v[168:171], v[198:199], off
	global_load_dwordx4 v[164:167], v[200:201], off
	global_load_dwordx4 v[152:155], v[206:207], off
	global_load_dwordx4 v[232:235], v[202:203], off
	global_load_dwordx4 v[228:231], v[196:197], off
	global_load_dword v179, v[194:195], off offset:256
	global_load_dword v181, v[198:199], off offset:256
	global_load_dword v183, v[200:201], off offset:256
	global_load_dword v185, v[206:207], off offset:256
	global_load_dword v187, v[202:203], off offset:256
	global_load_dword v253, v[196:197], off offset:256
	s_nop 0
	s_nop 0
	s_nop 0
	s_nop 0
	v_or_b32_e32 v193, v211, v219
	v_lshlrev_b32_e32 v193, 2, v193
	v_or_b32_e32 v225, v219, v212
	v_lshlrev_b32_e32 v225, 2, v225
	s_add_i32 s12, s0, 0x80
	s_cmpk_lt_i32 s12, 0x2000
	s_cselect_b32 s13, s20, 0x7ff
	s_addk_i32 s0, 0xbf
	s_and_b32 s14, s13, s12
	s_and_b32 s15, s13, s0
	s_cmp_eq_u32 s14, 0
	s_waitcnt vmcnt(0)
	ds_bpermute_b32 v239, v193, v172
	ds_bpermute_b32 v240, v193, v173
	ds_bpermute_b32 v241, v193, v174
	ds_bpermute_b32 v242, v193, v175
	ds_bpermute_b32 v243, v225, v168
	ds_bpermute_b32 v244, v225, v169
	ds_bpermute_b32 v245, v225, v170
	v_cndmask_b32_e64 v227, v235, 0, s[50:51]
	v_cndmask_b32_e64 v236, v230, 0, s[62:63]
	v_cndmask_b32_e64 v237, v229, 0, s[62:63]
	v_cndmask_b32_e64 v229, v233, 0, s[50:51]
	v_cndmask_b32_e64 v230, v232, 0, s[50:51]
	ds_bpermute_b32 v232, v225, v172
	ds_bpermute_b32 v233, v225, v173
	v_cndmask_b32_e64 v238, v228, 0, s[62:63]
	v_cndmask_b32_e64 v228, v234, 0, s[50:51]
	ds_bpermute_b32 v234, v225, v174
	ds_bpermute_b32 v235, v225, v175
	ds_bpermute_b32 v246, v225, v171
	s_waitcnt lgkmcnt(11)
	v_cndmask_b32_e64 v238, v239, v238, s[4:5]
	s_waitcnt lgkmcnt(4)
	v_cndmask_b32_e64 v247, v232, v243, s[6:7]
	s_waitcnt lgkmcnt(3)
	v_cndmask_b32_e64 v249, v233, v244, s[6:7]
	v_lshlrev_b32_e32 v232, 16, v238
	v_and_b32_e32 v233, 0xffff0000, v238
	v_cndmask_b32_e64 v248, v240, v237, s[4:5]
	v_cndmask_b32_e64 v250, v241, v236, s[4:5]
	v_pk_mul_f32 v[232:233], v[120:121], v[232:233]
	v_lshlrev_b32_e32 v236, 16, v172
	v_and_b32_e32 v237, 0xffff0000, v172
	s_waitcnt lgkmcnt(2)
	v_cndmask_b32_e64 v251, v234, v245, s[6:7]
	s_waitcnt lgkmcnt(0)
	v_cndmask_b32_e64 v252, v235, v246, s[6:7]
	v_lshlrev_b32_e32 v234, 16, v247
	v_and_b32_e32 v235, 0xffff0000, v247
	v_pk_fma_f32 v[232:233], v[112:113], v[236:237], v[232:233]
	v_cndmask_b32_e64 v231, v231, 0, s[62:63]
	v_pk_fma_f32 v[232:233], v[108:109], v[234:235], v[232:233]
	v_cndmask_b32_e64 v231, v242, v231, s[4:5]
	v_pk_add_f32 v[232:233], v[116:117], v[232:233]
	ds_bpermute_b32 v236, v225, v166
	v_mul_f32_e32 v172, 0xbfb8aa3b, v232
	v_exp_f32_e32 v172, v172
	ds_bpermute_b32 v237, v225, v167
	v_add_f32_e32 v172, 1.0, v172
	v_rcp_f32_e32 v234, v172
	v_mul_f32_e32 v172, 0xbfb8aa3b, v233
	v_exp_f32_e32 v172, v172
	s_nop 0
	v_add_f32_e32 v172, 1.0, v172
	v_rcp_f32_e32 v235, v172
	v_lshlrev_b32_e32 v172, 16, v173
	v_and_b32_e32 v173, 0xffff0000, v173
	v_pk_mul_f32 v[232:233], v[232:233], v[234:235]
	s_nop 0
	v_pk_mul_f32 v[160:161], v[160:161], v[232:233]
	v_lshlrev_b32_e32 v232, 16, v248
	v_and_b32_e32 v233, 0xffff0000, v248
	v_pk_mul_f32 v[232:233], v[122:123], v[232:233]
	v_lshlrev_b32_e32 v234, 16, v249
	v_and_b32_e32 v235, 0xffff0000, v249
	v_pk_fma_f32 v[172:173], v[114:115], v[172:173], v[232:233]
	s_nop 0
	v_pk_fma_f32 v[172:173], v[110:111], v[234:235], v[172:173]
	v_lshlrev_b32_e32 v234, 16, v174
	v_pk_add_f32 v[172:173], v[118:119], v[172:173]
	v_and_b32_e32 v235, 0xffff0000, v174
	v_mul_f32_e32 v232, 0xbfb8aa3b, v172
	v_mul_f32_e32 v233, 0xbfb8aa3b, v173
	v_exp_f32_e32 v232, v232
	v_exp_f32_e32 v233, v233
	v_add_f32_e32 v232, 1.0, v232
	v_add_f32_e32 v233, 1.0, v233
	v_rcp_f32_e32 v232, v232
	v_rcp_f32_e32 v233, v233
	s_nop 0
	v_pk_mul_f32 v[172:173], v[172:173], v[232:233]
	s_nop 0
	v_pk_mul_f32 v[162:163], v[162:163], v[172:173]
	v_lshlrev_b32_e32 v172, 16, v250
	v_and_b32_e32 v173, 0xffff0000, v250
	v_pk_mul_f32 v[172:173], v[100:101], v[172:173]
	v_lshlrev_b32_e32 v232, 16, v251
	v_and_b32_e32 v233, 0xffff0000, v251
	v_pk_fma_f32 v[172:173], v[92:93], v[234:235], v[172:173]
	ds_bpermute_b32 v234, v225, v164
	v_pk_fma_f32 v[172:173], v[88:89], v[232:233], v[172:173]
	ds_bpermute_b32 v235, v225, v165
	v_pk_add_f32 v[172:173], v[96:97], v[172:173]
	s_nop 0
	v_mul_f32_e32 v174, 0xbfb8aa3b, v172
	v_exp_f32_e32 v174, v174
	s_nop 0
	v_add_f32_e32 v174, 1.0, v174
	v_rcp_f32_e32 v232, v174
	v_mul_f32_e32 v174, 0xbfb8aa3b, v173
	v_exp_f32_e32 v174, v174
	s_nop 0
	v_add_f32_e32 v174, 1.0, v174
	v_rcp_f32_e32 v233, v174
	v_lshlrev_b32_e32 v174, 16, v175
	v_and_b32_e32 v175, 0xffff0000, v175
	v_pk_mul_f32 v[172:173], v[172:173], v[232:233]
	s_nop 0
	v_pk_mul_f32 v[156:157], v[156:157], v[172:173]
	v_lshlrev_b32_e32 v172, 16, v231
	v_and_b32_e32 v173, 0xffff0000, v231
	v_pk_mul_f32 v[172:173], v[102:103], v[172:173]
	v_lshlrev_b32_e32 v232, 16, v252
	v_and_b32_e32 v233, 0xffff0000, v252
	v_pk_fma_f32 v[172:173], v[94:95], v[174:175], v[172:173]
	ds_bpermute_b32 v231, v193, v170
	v_pk_fma_f32 v[172:173], v[90:91], v[232:233], v[172:173]
	ds_bpermute_b32 v232, v193, v171
	v_pk_add_f32 v[172:173], v[98:99], v[172:173]
	v_or_b32_e32 v233, 16, v226
	v_mul_f32_e32 v174, 0xbfb8aa3b, v172
	v_mul_f32_e32 v175, 0xbfb8aa3b, v173
	v_exp_f32_e32 v174, v174
	v_exp_f32_e32 v175, v175
	s_waitcnt lgkmcnt(0)
	v_cndmask_b32_e64 v242, v232, v242, s[4:5]
	v_add_f32_e32 v174, 1.0, v174
	v_add_f32_e32 v175, 1.0, v175
	v_rcp_f32_e32 v174, v174
	v_rcp_f32_e32 v175, v175
	s_nop 0
	v_pk_mul_f32 v[172:173], v[172:173], v[174:175]
	ds_bpermute_b32 v174, v193, v168
	v_pk_mul_f32 v[172:173], v[158:159], v[172:173]
	v_cvt_pk_bf16_f32 v158, v160, v161
	v_cvt_pk_bf16_f32 v161, v172, v173
	v_mov_b64_e32 v[172:173], s[16:17]
	v_cvt_pk_bf16_f32 v160, v156, v157
	v_mad_i64_i32 v[156:157], s[2:3], v226, s26, v[172:173]
	v_cvt_pk_bf16_f32 v159, v162, v163
	v_lshl_add_u64 v[156:157], v[156:157], 0, v[204:205]
	global_store_dwordx4 v[156:157], v[158:161], off
	v_lshlrev_b32_e32 v162, 16, v168
	v_and_b32_e32 v163, 0xffff0000, v168
	s_waitcnt lgkmcnt(0)
	v_cndmask_b32_e64 v159, v174, v239, s[4:5]
	v_lshlrev_b32_e32 v158, 16, v159
	v_and_b32_e32 v159, 0xffff0000, v159
	v_cndmask_b32_e64 v161, v243, v234, s[6:7]
	v_pk_mul_f32 v[158:159], v[120:121], v[158:159]
	v_lshlrev_b32_e32 v160, 16, v161
	v_and_b32_e32 v161, 0xffff0000, v161
	v_pk_fma_f32 v[158:159], v[112:113], v[162:163], v[158:159]
	ds_bpermute_b32 v175, v193, v169
	v_pk_fma_f32 v[158:159], v[108:109], v[160:161], v[158:159]
	v_cndmask_b32_e64 v239, v244, v235, s[6:7]
	v_pk_add_f32 v[158:159], v[116:117], v[158:159]
	v_lshlrev_b32_e32 v162, 16, v169
	v_mul_f32_e32 v160, 0xbfb8aa3b, v158
	v_mul_f32_e32 v161, 0xbfb8aa3b, v159
	v_exp_f32_e32 v160, v160
	v_exp_f32_e32 v161, v161
	s_waitcnt lgkmcnt(0)
	v_cndmask_b32_e64 v238, v175, v240, s[4:5]
	v_and_b32_e32 v163, 0xffff0000, v169
	v_add_f32_e32 v160, 1.0, v160
	v_add_f32_e32 v161, 1.0, v161
	v_rcp_f32_e32 v160, v160
	v_rcp_f32_e32 v161, v161
	v_cndmask_b32_e64 v240, v231, v241, s[4:5]
	v_cndmask_b32_e64 v241, v245, v236, s[6:7]
	v_cndmask_b32_e64 v243, v246, v237, s[6:7]
	v_pk_mul_f32 v[158:159], v[158:159], v[160:161]
	v_lshlrev_b32_e32 v160, 16, v239
	v_pk_mul_f32 v[148:149], v[148:149], v[158:159]
	v_lshlrev_b32_e32 v158, 16, v238
	v_and_b32_e32 v159, 0xffff0000, v238
	v_pk_mul_f32 v[158:159], v[122:123], v[158:159]
	v_and_b32_e32 v161, 0xffff0000, v239
	v_pk_fma_f32 v[158:159], v[114:115], v[162:163], v[158:159]
	v_lshlrev_b32_e32 v162, 16, v170
	v_pk_fma_f32 v[158:159], v[110:111], v[160:161], v[158:159]
	v_and_b32_e32 v163, 0xffff0000, v170
	v_pk_add_f32 v[158:159], v[118:119], v[158:159]
	v_cvt_pk_bf16_f32 v148, v148, v149
	v_mul_f32_e32 v160, 0xbfb8aa3b, v158
	v_mul_f32_e32 v161, 0xbfb8aa3b, v159
	v_exp_f32_e32 v160, v160
	v_exp_f32_e32 v161, v161
	ds_bpermute_b32 v168, v225, v153
	ds_bpermute_b32 v169, v225, v154
	v_add_f32_e32 v160, 1.0, v160
	v_add_f32_e32 v161, 1.0, v161
	v_rcp_f32_e32 v160, v160
	v_rcp_f32_e32 v161, v161
	ds_bpermute_b32 v170, v225, v155
	v_pk_mul_f32 v[158:159], v[158:159], v[160:161]
	s_nop 0
	v_pk_mul_f32 v[150:151], v[150:151], v[158:159]
	v_lshlrev_b32_e32 v158, 16, v240
	v_and_b32_e32 v159, 0xffff0000, v240
	v_pk_mul_f32 v[158:159], v[100:101], v[158:159]
	v_lshlrev_b32_e32 v160, 16, v241
	v_and_b32_e32 v161, 0xffff0000, v241
	v_pk_fma_f32 v[158:159], v[92:93], v[162:163], v[158:159]
	v_lshlrev_b32_e32 v162, 16, v171
	v_pk_fma_f32 v[158:159], v[88:89], v[160:161], v[158:159]
	v_and_b32_e32 v163, 0xffff0000, v171
	v_pk_add_f32 v[158:159], v[96:97], v[158:159]
	v_cvt_pk_bf16_f32 v149, v150, v151
	v_mul_f32_e32 v160, 0xbfb8aa3b, v158
	v_mul_f32_e32 v161, 0xbfb8aa3b, v159
	v_exp_f32_e32 v160, v160
	v_exp_f32_e32 v161, v161
	v_add_f32_e32 v160, 1.0, v160
	v_add_f32_e32 v161, 1.0, v161
	v_rcp_f32_e32 v160, v160
	v_rcp_f32_e32 v161, v161
	s_nop 0
	v_pk_mul_f32 v[158:159], v[158:159], v[160:161]
	s_nop 0
	v_pk_mul_f32 v[144:145], v[144:145], v[158:159]
	v_lshlrev_b32_e32 v158, 16, v242
	v_and_b32_e32 v159, 0xffff0000, v242
	v_pk_mul_f32 v[158:159], v[102:103], v[158:159]
	v_lshlrev_b32_e32 v160, 16, v243
	v_and_b32_e32 v161, 0xffff0000, v243
	v_pk_fma_f32 v[158:159], v[94:95], v[162:163], v[158:159]
	ds_bpermute_b32 v163, v225, v152
	v_pk_fma_f32 v[158:159], v[90:91], v[160:161], v[158:159]
	v_cvt_pk_bf16_f32 v150, v144, v145
	v_pk_add_f32 v[158:159], v[98:99], v[158:159]
	v_mad_i64_i32 v[144:145], s[2:3], v233, s26, v[172:173]
	v_mul_f32_e32 v160, 0xbfb8aa3b, v158
	v_mul_f32_e32 v161, 0xbfb8aa3b, v159
	v_exp_f32_e32 v160, v160
	v_exp_f32_e32 v161, v161
	s_waitcnt lgkmcnt(1)
	v_cndmask_b32_e64 v233, v237, v170, s[6:7]
	v_or_b32_e32 v162, 32, v226
	v_add_f32_e32 v160, 1.0, v160
	v_add_f32_e32 v161, 1.0, v161
	v_rcp_f32_e32 v160, v160
	v_rcp_f32_e32 v161, v161
	s_nop 0
	v_pk_mul_f32 v[158:159], v[158:159], v[160:161]
	s_nop 0
	v_pk_mul_f32 v[146:147], v[146:147], v[158:159]
	ds_bpermute_b32 v158, v193, v164
	v_cvt_pk_bf16_f32 v151, v146, v147
	v_lshl_add_u64 v[146:147], v[144:145], 0, v[204:205]
	global_store_dwordx4 v[146:147], v[148:151], off
	ds_bpermute_b32 v159, v193, v165
	s_waitcnt lgkmcnt(1)
	v_cndmask_b32_e64 v145, v158, v174, s[4:5]
	v_lshlrev_b32_e32 v144, 16, v145
	v_and_b32_e32 v145, 0xffff0000, v145
	v_cndmask_b32_e64 v149, v234, v163, s[6:7]
	v_pk_mul_f32 v[144:145], v[120:121], v[144:145]
	v_lshlrev_b32_e32 v150, 16, v164
	v_and_b32_e32 v151, 0xffff0000, v164
	v_lshlrev_b32_e32 v148, 16, v149
	v_and_b32_e32 v149, 0xffff0000, v149
	v_pk_fma_f32 v[144:145], v[112:113], v[150:151], v[144:145]
	s_waitcnt lgkmcnt(0)
	v_cndmask_b32_e64 v171, v159, v175, s[4:5]
	v_pk_fma_f32 v[144:145], v[108:109], v[148:149], v[144:145]
	v_cndmask_b32_e64 v174, v235, v168, s[6:7]
	v_pk_add_f32 v[144:145], v[116:117], v[144:145]
	v_lshlrev_b32_e32 v150, 16, v165
	v_mul_f32_e32 v148, 0xbfb8aa3b, v144
	v_mul_f32_e32 v149, 0xbfb8aa3b, v145
	v_exp_f32_e32 v148, v148
	v_exp_f32_e32 v149, v149
	v_and_b32_e32 v151, 0xffff0000, v165
	ds_bpermute_b32 v160, v193, v166
	v_add_f32_e32 v148, 1.0, v148
	v_add_f32_e32 v149, 1.0, v149
	v_rcp_f32_e32 v148, v148
	v_rcp_f32_e32 v149, v149
	s_waitcnt lgkmcnt(0)
	v_cndmask_b32_e64 v175, v160, v231, s[4:5]
	v_cndmask_b32_e64 v231, v236, v169, s[6:7]
	ds_bpermute_b32 v161, v193, v167
	v_pk_mul_f32 v[144:145], v[144:145], v[148:149]
	v_lshlrev_b32_e32 v148, 16, v174
	v_pk_mul_f32 v[140:141], v[140:141], v[144:145]
	v_lshlrev_b32_e32 v144, 16, v171
	v_and_b32_e32 v145, 0xffff0000, v171
	v_pk_mul_f32 v[144:145], v[122:123], v[144:145]
	v_and_b32_e32 v149, 0xffff0000, v174
	v_pk_fma_f32 v[144:145], v[114:115], v[150:151], v[144:145]
	v_lshlrev_b32_e32 v150, 16, v166
	v_pk_fma_f32 v[144:145], v[110:111], v[148:149], v[144:145]
	v_and_b32_e32 v151, 0xffff0000, v166
	v_pk_add_f32 v[144:145], v[118:119], v[144:145]
	s_waitcnt lgkmcnt(0)
	v_cndmask_b32_e64 v232, v161, v232, s[4:5]
	v_mul_f32_e32 v148, 0xbfb8aa3b, v144
	v_mul_f32_e32 v149, 0xbfb8aa3b, v145
	v_exp_f32_e32 v148, v148
	v_exp_f32_e32 v149, v149
	v_or_b32_e32 v164, s12, v221
	v_add_f32_e32 v148, 1.0, v148
	v_add_f32_e32 v149, 1.0, v149
	v_rcp_f32_e32 v148, v148
	v_rcp_f32_e32 v149, v149
	s_nop 0
	v_pk_mul_f32 v[144:145], v[144:145], v[148:149]
	s_nop 0
	v_pk_mul_f32 v[142:143], v[142:143], v[144:145]
	v_lshlrev_b32_e32 v144, 16, v175
	v_and_b32_e32 v145, 0xffff0000, v175
	v_pk_mul_f32 v[144:145], v[100:101], v[144:145]
	v_lshlrev_b32_e32 v148, 16, v231
	v_and_b32_e32 v149, 0xffff0000, v231
	v_pk_fma_f32 v[144:145], v[92:93], v[150:151], v[144:145]
	v_lshlrev_b32_e32 v150, 16, v167
	v_pk_fma_f32 v[144:145], v[88:89], v[148:149], v[144:145]
	v_and_b32_e32 v151, 0xffff0000, v167
	v_pk_add_f32 v[144:145], v[96:97], v[144:145]
	s_nop 0
	v_mul_f32_e32 v148, 0xbfb8aa3b, v144
	v_mul_f32_e32 v149, 0xbfb8aa3b, v145
	v_exp_f32_e32 v148, v148
	v_exp_f32_e32 v149, v149
	v_add_f32_e32 v148, 1.0, v148
	v_add_f32_e32 v149, 1.0, v149
	v_rcp_f32_e32 v148, v148
	v_rcp_f32_e32 v149, v149
	s_nop 0
	v_pk_mul_f32 v[144:145], v[144:145], v[148:149]
	s_nop 0
	v_pk_mul_f32 v[144:145], v[136:137], v[144:145]
	v_lshlrev_b32_e32 v136, 16, v232
	v_and_b32_e32 v137, 0xffff0000, v232
	v_pk_mul_f32 v[136:137], v[102:103], v[136:137]
	v_lshlrev_b32_e32 v148, 16, v233
	v_and_b32_e32 v149, 0xffff0000, v233
	v_pk_fma_f32 v[136:137], v[94:95], v[150:151], v[136:137]
	v_cndmask_b32_e64 v150, v169, v228, s[6:7]
	v_pk_fma_f32 v[136:137], v[90:91], v[148:149], v[136:137]
	s_nop 0
	v_pk_add_f32 v[136:137], v[98:99], v[136:137]
	s_nop 0
	v_mul_f32_e32 v148, 0xbfb8aa3b, v136
	v_mul_f32_e32 v149, 0xbfb8aa3b, v137
	v_exp_f32_e32 v148, v148
	v_exp_f32_e32 v149, v149
	v_add_f32_e32 v148, 1.0, v148
	v_add_f32_e32 v149, 1.0, v149
	v_rcp_f32_e32 v148, v148
	v_rcp_f32_e32 v149, v149
	s_nop 0
	v_pk_mul_f32 v[136:137], v[136:137], v[148:149]
	s_nop 0
	v_pk_mul_f32 v[148:149], v[138:139], v[136:137]
	v_cvt_pk_bf16_f32 v136, v140, v141
	v_mad_i64_i32 v[140:141], s[2:3], v162, s26, v[172:173]
	v_cvt_pk_bf16_f32 v137, v142, v143
	v_cvt_pk_bf16_f32 v138, v144, v145
	v_cvt_pk_bf16_f32 v139, v148, v149
	v_lshl_add_u64 v[148:149], v[140:141], 0, v[204:205]
	global_store_dwordx4 v[148:149], v[136:139], off
	ds_bpermute_b32 v136, v193, v152
	ds_bpermute_b32 v137, v193, v153
	ds_bpermute_b32 v138, v193, v154
	ds_bpermute_b32 v139, v193, v155
	v_cndmask_b32_e64 v141, v163, v230, s[6:7]
	s_waitcnt lgkmcnt(3)
	v_cndmask_b32_e64 v140, v136, v158, s[4:5]
	s_waitcnt lgkmcnt(2)
	v_cndmask_b32_e64 v143, v137, v159, s[4:5]
	v_lshlrev_b32_e32 v136, 16, v140
	v_and_b32_e32 v137, 0xffff0000, v140
	s_waitcnt lgkmcnt(1)
	v_cndmask_b32_e64 v145, v138, v160, s[4:5]
	s_waitcnt lgkmcnt(0)
	v_cndmask_b32_e64 v151, v139, v161, s[4:5]
	v_lshlrev_b32_e32 v138, 16, v141
	v_and_b32_e32 v139, 0xffff0000, v141
	v_pk_mul_f32 v[136:137], v[120:121], v[136:137]
	v_lshlrev_b32_e32 v140, 16, v152
	v_and_b32_e32 v141, 0xffff0000, v152
	v_pk_fma_f32 v[136:137], v[112:113], v[140:141], v[136:137]
	v_cndmask_b32_e64 v144, v168, v229, s[6:7]
	v_pk_fma_f32 v[136:137], v[108:109], v[138:139], v[136:137]
	v_lshlrev_b32_e32 v140, 16, v153
	v_pk_add_f32 v[136:137], v[116:117], v[136:137]
	v_and_b32_e32 v141, 0xffff0000, v153
	v_mul_f32_e32 v138, 0xbfb8aa3b, v136
	v_mul_f32_e32 v139, 0xbfb8aa3b, v137
	v_exp_f32_e32 v138, v138
	v_exp_f32_e32 v139, v139
	v_cndmask_b32_e64 v158, v170, v227, s[6:7]
	v_or_b32_e32 v142, 48, v226
	v_add_f32_e32 v138, 1.0, v138
	v_add_f32_e32 v139, 1.0, v139
	v_rcp_f32_e32 v138, v138
	v_rcp_f32_e32 v139, v139
	s_nop 0
	v_pk_mul_f32 v[136:137], v[136:137], v[138:139]
	s_nop 0
	v_pk_mul_f32 v[132:133], v[132:133], v[136:137]
	v_lshlrev_b32_e32 v136, 16, v143
	v_and_b32_e32 v137, 0xffff0000, v143
	v_pk_mul_f32 v[136:137], v[122:123], v[136:137]
	v_lshlrev_b32_e32 v138, 16, v144
	v_and_b32_e32 v139, 0xffff0000, v144
	v_pk_fma_f32 v[136:137], v[114:115], v[140:141], v[136:137]
	v_lshlrev_b32_e32 v140, 16, v154
	v_pk_fma_f32 v[136:137], v[110:111], v[138:139], v[136:137]
	v_and_b32_e32 v141, 0xffff0000, v154
	v_pk_add_f32 v[136:137], v[118:119], v[136:137]
	s_nop 0
	v_mul_f32_e32 v138, 0xbfb8aa3b, v136
	v_mul_f32_e32 v139, 0xbfb8aa3b, v137
	v_exp_f32_e32 v138, v138
	v_exp_f32_e32 v139, v139
	v_add_f32_e32 v138, 1.0, v138
	v_add_f32_e32 v139, 1.0, v139
	v_rcp_f32_e32 v138, v138
	v_rcp_f32_e32 v139, v139
	s_nop 0
	v_pk_mul_f32 v[136:137], v[136:137], v[138:139]
	s_nop 0
	v_pk_mul_f32 v[134:135], v[134:135], v[136:137]
	v_lshlrev_b32_e32 v136, 16, v145
	v_and_b32_e32 v137, 0xffff0000, v145
	v_pk_mul_f32 v[136:137], v[100:101], v[136:137]
	v_lshlrev_b32_e32 v138, 16, v150
	v_and_b32_e32 v139, 0xffff0000, v150
	v_pk_fma_f32 v[136:137], v[92:93], v[140:141], v[136:137]
	v_lshlrev_b32_e32 v140, 16, v155
	v_pk_fma_f32 v[136:137], v[88:89], v[138:139], v[136:137]
	v_and_b32_e32 v141, 0xffff0000, v155
	v_pk_add_f32 v[136:137], v[96:97], v[136:137]
	s_nop 0
	v_mul_f32_e32 v138, 0xbfb8aa3b, v136
	v_mul_f32_e32 v139, 0xbfb8aa3b, v137
	v_exp_f32_e32 v138, v138
	v_exp_f32_e32 v139, v139
	v_add_f32_e32 v138, 1.0, v138
	v_add_f32_e32 v139, 1.0, v139
	v_rcp_f32_e32 v138, v138
	v_rcp_f32_e32 v139, v139
	s_nop 0
	v_pk_mul_f32 v[136:137], v[136:137], v[138:139]
	s_nop 0
	v_pk_mul_f32 v[136:137], v[128:129], v[136:137]
	v_lshlrev_b32_e32 v128, 16, v151
	v_and_b32_e32 v129, 0xffff0000, v151
	v_pk_mul_f32 v[128:129], v[102:103], v[128:129]
	v_lshlrev_b32_e32 v138, 16, v158
	v_and_b32_e32 v139, 0xffff0000, v158
	v_pk_fma_f32 v[128:129], v[94:95], v[140:141], v[128:129]
	s_nop 0
	v_pk_fma_f32 v[128:129], v[90:91], v[138:139], v[128:129]
	s_nop 0
	v_pk_add_f32 v[128:129], v[98:99], v[128:129]
	s_nop 0
	v_mul_f32_e32 v138, 0xbfb8aa3b, v128
	v_mul_f32_e32 v139, 0xbfb8aa3b, v129
	v_exp_f32_e32 v138, v138
	v_exp_f32_e32 v139, v139
	v_add_f32_e32 v138, 1.0, v138
	v_add_f32_e32 v139, 1.0, v139
	v_rcp_f32_e32 v138, v138
	v_rcp_f32_e32 v139, v139
	s_nop 0
	v_pk_mul_f32 v[128:129], v[128:129], v[138:139]
	s_nop 0
	v_pk_mul_f32 v[138:139], v[130:131], v[128:129]
	v_cvt_pk_bf16_f32 v128, v132, v133
	v_mad_i64_i32 v[132:133], s[2:3], v142, s26, v[172:173]
	v_cvt_pk_bf16_f32 v129, v134, v135
	v_cvt_pk_bf16_f32 v130, v136, v137
	v_cvt_pk_bf16_f32 v131, v138, v139
	v_lshl_add_u64 v[144:145], v[132:133], 0, v[204:205]
	global_store_dwordx4 v[144:145], v[128:131], off
	s_nop 1
	v_mad_i64_i32 v[128:129], s[2:3], v164, s26, v[208:209]
	v_lshl_add_u64 v[150:151], v[128:129], 0, v[204:205]
	v_add_co_u32_e32 v152, vcc, s21, v150
	s_mul_hi_i32 s2, s12, 0x2c00
	s_nop 0
	v_addc_co_u32_e32 v153, vcc, 0, v151, vcc
	v_add_co_u32_e32 v154, vcc, s22, v150
	global_load_dwordx4 v[140:143], v[150:151], off
	global_load_dwordx4 v[136:139], v[152:153], off
	v_addc_co_u32_e32 v155, vcc, 0, v151, vcc
	v_add_co_u32_e32 v158, vcc, s23, v150
	s_cselect_b64 s[22:23], -1, 0
	s_add_i32 s1, s1, 0x160000
	s_add_u32 s0, s10, s1
	s_addc_u32 s1, s11, s2
	s_and_b64 s[2:3], s[22:23], exec
	v_addc_co_u32_e32 v159, vcc, 0, v151, vcc
	s_cselect_b32 s2, 0, 0xffffd400
	s_cselect_b32 s3, 0, -1
	s_cmp_eq_u32 s15, s13
	s_cselect_b64 vcc, -1, 0
	v_lshl_add_u64 v[160:161], s[0:1], 0, v[204:205]
	s_and_b64 s[0:1], vcc, exec
	s_cselect_b32 s72, 0, 0xb0000
	v_lshl_add_u64 v[162:163], v[160:161], 0, s[2:3]
	v_lshl_add_u64 v[160:161], v[160:161], 0, s[72:73]
	global_load_dwordx4 v[166:169], v[162:163], off
	global_load_dwordx4 v[226:229], v[160:161], off
	global_load_dwordx4 v[132:135], v[154:155], off
	global_load_dwordx4 v[128:131], v[158:159], off
	global_load_dword v179, v[150:151], off offset:256
	global_load_dword v181, v[152:153], off offset:256
	global_load_dword v183, v[162:163], off offset:256
	global_load_dword v185, v[160:161], off offset:256
	global_load_dword v187, v[154:155], off offset:256
	global_load_dword v253, v[158:159], off offset:256
	s_nop 0
	s_nop 0
	s_nop 0
	s_nop 0
	s_waitcnt vmcnt(5)
	ds_bpermute_b32 v175, v225, v140
	ds_bpermute_b32 v208, v225, v141
	ds_bpermute_b32 v209, v225, v142
	s_waitcnt vmcnt(4)
	ds_bpermute_b32 v231, v225, v136
	ds_bpermute_b32 v232, v225, v137
	ds_bpermute_b32 v233, v225, v138
	ds_bpermute_b32 v230, v225, v143
	ds_bpermute_b32 v234, v225, v139
	s_waitcnt lgkmcnt(4)
	v_cndmask_b32_e64 v175, v175, v231, s[6:7]
	s_waitcnt lgkmcnt(3)
	v_cndmask_b32_e64 v237, v208, v232, s[6:7]
	s_waitcnt lgkmcnt(2)
	v_cndmask_b32_e64 v239, v209, v233, s[6:7]
	v_lshlrev_b32_e32 v208, 16, v140
	v_and_b32_e32 v209, 0xffff0000, v140
	s_waitcnt lgkmcnt(0)
	v_cndmask_b32_e64 v230, v230, v234, s[6:7]
	s_waitcnt vmcnt(3)
	v_cndmask_b32_e64 v170, v168, 0, s[22:23]
	s_waitcnt vmcnt(2)
	v_cndmask_b32_e64 v168, v226, 0, vcc
	ds_bpermute_b32 v226, v193, v140
	v_cndmask_b32_e64 v171, v167, 0, s[22:23]
	v_cndmask_b32_e64 v174, v166, 0, s[22:23]
	v_cndmask_b32_e64 v166, v228, 0, vcc
	v_cndmask_b32_e64 v167, v227, 0, vcc
	ds_bpermute_b32 v227, v193, v141
	ds_bpermute_b32 v228, v193, v142
	s_waitcnt lgkmcnt(2)
	v_cndmask_b32_e64 v235, v226, v174, s[4:5]
	v_lshlrev_b32_e32 v174, 16, v175
	v_and_b32_e32 v175, 0xffff0000, v175
	s_waitcnt lgkmcnt(1)
	v_cndmask_b32_e64 v236, v227, v171, s[4:5]
	s_waitcnt lgkmcnt(0)
	v_cndmask_b32_e64 v238, v228, v170, s[4:5]
	v_lshlrev_b32_e32 v170, 16, v235
	v_and_b32_e32 v171, 0xffff0000, v235
	v_pk_mul_f32 v[170:171], v[120:121], v[170:171]
	v_cndmask_b32_e64 v165, v229, 0, vcc
	v_pk_fma_f32 v[170:171], v[112:113], v[208:209], v[170:171]
	ds_bpermute_b32 v229, v193, v143
	v_pk_fma_f32 v[170:171], v[108:109], v[174:175], v[170:171]
	v_cndmask_b32_e64 v169, v169, 0, s[22:23]
	v_pk_add_f32 v[170:171], v[116:117], v[170:171]
	s_waitcnt lgkmcnt(0)
	v_cndmask_b32_e64 v169, v229, v169, s[4:5]
	v_mul_f32_e32 v140, 0xbfb8aa3b, v170
	v_exp_f32_e32 v140, v140
	s_nop 0
	v_add_f32_e32 v140, 1.0, v140
	v_rcp_f32_e32 v174, v140
	v_mul_f32_e32 v140, 0xbfb8aa3b, v171
	v_exp_f32_e32 v140, v140
	s_nop 0
	v_add_f32_e32 v140, 1.0, v140
	v_rcp_f32_e32 v175, v140
	v_lshlrev_b32_e32 v140, 16, v141
	v_and_b32_e32 v141, 0xffff0000, v141
	v_pk_mul_f32 v[170:171], v[170:171], v[174:175]
	s_nop 0
	v_pk_mul_f32 v[124:125], v[124:125], v[170:171]
	v_lshlrev_b32_e32 v170, 16, v236
	v_and_b32_e32 v171, 0xffff0000, v236
	v_pk_mul_f32 v[170:171], v[122:123], v[170:171]
	v_lshlrev_b32_e32 v174, 16, v237
	v_and_b32_e32 v175, 0xffff0000, v237
	v_pk_fma_f32 v[140:141], v[114:115], v[140:141], v[170:171]
	s_nop 0
	v_pk_fma_f32 v[140:141], v[110:111], v[174:175], v[140:141]
	v_lshlrev_b32_e32 v174, 16, v142
	v_pk_add_f32 v[140:141], v[118:119], v[140:141]
	v_and_b32_e32 v175, 0xffff0000, v142
	v_mul_f32_e32 v170, 0xbfb8aa3b, v140
	v_mul_f32_e32 v171, 0xbfb8aa3b, v141
	v_exp_f32_e32 v170, v170
	v_exp_f32_e32 v171, v171
	v_add_f32_e32 v170, 1.0, v170
	v_add_f32_e32 v171, 1.0, v171
	v_rcp_f32_e32 v170, v170
	v_rcp_f32_e32 v171, v171
	s_nop 0
	v_pk_mul_f32 v[140:141], v[140:141], v[170:171]
	s_nop 0
	v_pk_mul_f32 v[126:127], v[126:127], v[140:141]
	v_lshlrev_b32_e32 v140, 16, v238
	v_and_b32_e32 v141, 0xffff0000, v238
	v_pk_mul_f32 v[140:141], v[100:101], v[140:141]
	v_lshlrev_b32_e32 v170, 16, v239
	v_and_b32_e32 v171, 0xffff0000, v239
	v_pk_fma_f32 v[140:141], v[92:93], v[174:175], v[140:141]
	s_waitcnt vmcnt(1)
	ds_bpermute_b32 v174, v225, v134
	v_pk_fma_f32 v[140:141], v[88:89], v[170:171], v[140:141]
	ds_bpermute_b32 v175, v225, v135
	v_pk_add_f32 v[140:141], v[96:97], v[140:141]
	s_nop 0
	v_mul_f32_e32 v142, 0xbfb8aa3b, v140
	v_exp_f32_e32 v142, v142
	s_nop 0
	v_add_f32_e32 v142, 1.0, v142
	v_rcp_f32_e32 v170, v142
	v_mul_f32_e32 v142, 0xbfb8aa3b, v141
	v_exp_f32_e32 v142, v142
	s_nop 0
	v_add_f32_e32 v142, 1.0, v142
	v_rcp_f32_e32 v171, v142
	v_lshlrev_b32_e32 v142, 16, v143
	v_and_b32_e32 v143, 0xffff0000, v143
	v_pk_mul_f32 v[140:141], v[140:141], v[170:171]
	s_nop 0
	v_pk_mul_f32 v[140:141], v[104:105], v[140:141]
	v_lshlrev_b32_e32 v104, 16, v169
	v_and_b32_e32 v105, 0xffff0000, v169
	v_pk_mul_f32 v[104:105], v[102:103], v[104:105]
	v_lshlrev_b32_e32 v170, 16, v230
	v_and_b32_e32 v171, 0xffff0000, v230
	v_pk_fma_f32 v[104:105], v[94:95], v[142:143], v[104:105]
	v_or_b32_e32 v169, 16, v164
	v_pk_fma_f32 v[104:105], v[90:91], v[170:171], v[104:105]
	ds_bpermute_b32 v170, v225, v132
	v_pk_add_f32 v[104:105], v[98:99], v[104:105]
	ds_bpermute_b32 v171, v225, v133
	v_mul_f32_e32 v142, 0xbfb8aa3b, v104
	v_mul_f32_e32 v143, 0xbfb8aa3b, v105
	v_exp_f32_e32 v142, v142
	v_exp_f32_e32 v143, v143
	s_waitcnt lgkmcnt(0)
	v_cndmask_b32_e64 v209, v232, v171, s[6:7]
	v_add_f32_e32 v142, 1.0, v142
	v_add_f32_e32 v143, 1.0, v143
	v_rcp_f32_e32 v142, v142
	v_rcp_f32_e32 v143, v143
	s_nop 0
	v_pk_mul_f32 v[104:105], v[104:105], v[142:143]
	s_nop 0
	v_pk_mul_f32 v[142:143], v[106:107], v[104:105]
	v_cvt_pk_bf16_f32 v106, v140, v141
	ds_bpermute_b32 v140, v193, v136
	v_cvt_pk_bf16_f32 v104, v124, v125
	v_mad_i64_i32 v[124:125], s[0:1], v164, s26, v[172:173]
	v_cvt_pk_bf16_f32 v105, v126, v127
	v_cvt_pk_bf16_f32 v107, v142, v143
	v_lshl_add_u64 v[124:125], v[124:125], 0, v[204:205]
	global_store_dwordx4 v[124:125], v[104:107], off
	v_lshlrev_b32_e32 v126, 16, v136
	v_and_b32_e32 v127, 0xffff0000, v136
	s_waitcnt lgkmcnt(0)
	v_cndmask_b32_e64 v105, v140, v226, s[4:5]
	v_lshlrev_b32_e32 v104, 16, v105
	v_and_b32_e32 v105, 0xffff0000, v105
	v_cndmask_b32_e64 v107, v231, v170, s[6:7]
	v_pk_mul_f32 v[104:105], v[120:121], v[104:105]
	v_lshlrev_b32_e32 v106, 16, v107
	v_and_b32_e32 v107, 0xffff0000, v107
	v_pk_fma_f32 v[104:105], v[112:113], v[126:127], v[104:105]
	ds_bpermute_b32 v141, v193, v137
	v_pk_fma_f32 v[104:105], v[108:109], v[106:107], v[104:105]
	v_lshlrev_b32_e32 v126, 16, v137
	v_pk_add_f32 v[104:105], v[116:117], v[104:105]
	v_and_b32_e32 v127, 0xffff0000, v137
	v_mul_f32_e32 v106, 0xbfb8aa3b, v104
	v_mul_f32_e32 v107, 0xbfb8aa3b, v105
	v_exp_f32_e32 v106, v106
	v_exp_f32_e32 v107, v107
	s_waitcnt lgkmcnt(0)
	v_cndmask_b32_e64 v208, v141, v227, s[4:5]
	ds_bpermute_b32 v142, v193, v138
	v_add_f32_e32 v106, 1.0, v106
	v_add_f32_e32 v107, 1.0, v107
	v_rcp_f32_e32 v106, v106
	v_rcp_f32_e32 v107, v107
	s_waitcnt lgkmcnt(0)
	v_cndmask_b32_e64 v226, v142, v228, s[4:5]
	v_cndmask_b32_e64 v227, v233, v174, s[6:7]
	ds_bpermute_b32 v143, v193, v139
	v_pk_mul_f32 v[104:105], v[104:105], v[106:107]
	v_lshlrev_b32_e32 v106, 16, v209
	v_pk_mul_f32 v[84:85], v[84:85], v[104:105]
	v_lshlrev_b32_e32 v104, 16, v208
	v_and_b32_e32 v105, 0xffff0000, v208
	v_pk_mul_f32 v[104:105], v[122:123], v[104:105]
	v_and_b32_e32 v107, 0xffff0000, v209
	v_pk_fma_f32 v[104:105], v[114:115], v[126:127], v[104:105]
	v_lshlrev_b32_e32 v126, 16, v138
	v_pk_fma_f32 v[104:105], v[110:111], v[106:107], v[104:105]
	v_and_b32_e32 v127, 0xffff0000, v138
	v_pk_add_f32 v[104:105], v[118:119], v[104:105]
	s_waitcnt lgkmcnt(0)
	v_cndmask_b32_e64 v228, v143, v229, s[4:5]
	v_mul_f32_e32 v106, 0xbfb8aa3b, v104
	v_mul_f32_e32 v107, 0xbfb8aa3b, v105
	v_exp_f32_e32 v106, v106
	v_exp_f32_e32 v107, v107
	v_cndmask_b32_e64 v229, v234, v175, s[6:7]
	s_waitcnt vmcnt(1)
	ds_bpermute_b32 v136, v225, v129
	v_add_f32_e32 v106, 1.0, v106
	v_add_f32_e32 v107, 1.0, v107
	v_rcp_f32_e32 v106, v106
	v_rcp_f32_e32 v107, v107
	ds_bpermute_b32 v137, v225, v130
	ds_bpermute_b32 v138, v225, v131
	v_pk_mul_f32 v[104:105], v[104:105], v[106:107]
	s_nop 0
	v_pk_mul_f32 v[86:87], v[86:87], v[104:105]
	v_lshlrev_b32_e32 v104, 16, v226
	v_and_b32_e32 v105, 0xffff0000, v226
	v_pk_mul_f32 v[104:105], v[100:101], v[104:105]
	v_lshlrev_b32_e32 v106, 16, v227
	v_and_b32_e32 v107, 0xffff0000, v227
	v_pk_fma_f32 v[104:105], v[92:93], v[126:127], v[104:105]
	v_lshlrev_b32_e32 v126, 16, v139
	v_pk_fma_f32 v[104:105], v[88:89], v[106:107], v[104:105]
	v_and_b32_e32 v127, 0xffff0000, v139
	v_pk_add_f32 v[104:105], v[96:97], v[104:105]
	s_nop 0
	v_mul_f32_e32 v106, 0xbfb8aa3b, v104
	v_mul_f32_e32 v107, 0xbfb8aa3b, v105
	v_exp_f32_e32 v106, v106
	v_exp_f32_e32 v107, v107
	v_add_f32_e32 v106, 1.0, v106
	v_add_f32_e32 v107, 1.0, v107
	v_rcp_f32_e32 v106, v106
	v_rcp_f32_e32 v107, v107
	s_nop 0
	v_pk_mul_f32 v[104:105], v[104:105], v[106:107]
	s_nop 0
	v_pk_mul_f32 v[104:105], v[80:81], v[104:105]
	v_lshlrev_b32_e32 v80, 16, v228
	v_and_b32_e32 v81, 0xffff0000, v228
	v_pk_mul_f32 v[80:81], v[102:103], v[80:81]
	v_lshlrev_b32_e32 v106, 16, v229
	v_and_b32_e32 v107, 0xffff0000, v229
	v_pk_fma_f32 v[80:81], v[94:95], v[126:127], v[80:81]
	s_nop 0
	v_pk_fma_f32 v[80:81], v[90:91], v[106:107], v[80:81]
	s_nop 0
	v_pk_add_f32 v[80:81], v[98:99], v[80:81]
	s_nop 0
	v_mul_f32_e32 v106, 0xbfb8aa3b, v80
	v_mul_f32_e32 v107, 0xbfb8aa3b, v81
	v_exp_f32_e32 v106, v106
	v_exp_f32_e32 v107, v107
	v_add_f32_e32 v106, 1.0, v106
	v_add_f32_e32 v107, 1.0, v107
	v_rcp_f32_e32 v106, v106
	v_rcp_f32_e32 v107, v107
	s_nop 0
	v_pk_mul_f32 v[80:81], v[80:81], v[106:107]
	s_nop 0
	v_pk_mul_f32 v[106:107], v[82:83], v[80:81]
	v_cvt_pk_bf16_f32 v81, v86, v87
	ds_bpermute_b32 v86, v193, v132
	v_cvt_pk_bf16_f32 v83, v106, v107
	ds_bpermute_b32 v107, v225, v128
	v_cvt_pk_bf16_f32 v80, v84, v85
	v_mad_i64_i32 v[84:85], s[0:1], v169, s26, v[172:173]
	v_cvt_pk_bf16_f32 v82, v104, v105
	v_lshl_add_u64 v[126:127], v[84:85], 0, v[204:205]
	global_store_dwordx4 v[126:127], v[80:83], off
	v_lshlrev_b32_e32 v84, 16, v132
	v_and_b32_e32 v85, 0xffff0000, v132
	s_waitcnt lgkmcnt(1)
	v_cndmask_b32_e64 v81, v86, v140, s[4:5]
	v_lshlrev_b32_e32 v80, 16, v81
	v_and_b32_e32 v81, 0xffff0000, v81
	s_waitcnt lgkmcnt(0)
	v_cndmask_b32_e64 v83, v170, v107, s[6:7]
	v_pk_mul_f32 v[80:81], v[120:121], v[80:81]
	v_lshlrev_b32_e32 v82, 16, v83
	v_and_b32_e32 v83, 0xffff0000, v83
	v_pk_fma_f32 v[80:81], v[112:113], v[84:85], v[80:81]
	ds_bpermute_b32 v87, v193, v133
	v_pk_fma_f32 v[80:81], v[108:109], v[82:83], v[80:81]
	v_cndmask_b32_e64 v140, v171, v136, s[6:7]
	v_pk_add_f32 v[80:81], v[116:117], v[80:81]
	v_lshlrev_b32_e32 v84, 16, v133
	v_mul_f32_e32 v82, 0xbfb8aa3b, v80
	v_mul_f32_e32 v83, 0xbfb8aa3b, v81
	v_exp_f32_e32 v82, v82
	v_exp_f32_e32 v83, v83
	s_waitcnt lgkmcnt(0)
	v_cndmask_b32_e64 v139, v87, v141, s[4:5]
	v_and_b32_e32 v85, 0xffff0000, v133
	v_add_f32_e32 v82, 1.0, v82
	v_add_f32_e32 v83, 1.0, v83
	v_rcp_f32_e32 v82, v82
	v_rcp_f32_e32 v83, v83
	ds_bpermute_b32 v104, v193, v134
	ds_bpermute_b32 v105, v193, v135
	v_cndmask_b32_e64 v169, v175, v138, s[6:7]
	v_pk_mul_f32 v[80:81], v[80:81], v[82:83]
	v_lshlrev_b32_e32 v82, 16, v140
	v_pk_mul_f32 v[76:77], v[76:77], v[80:81]
	v_lshlrev_b32_e32 v80, 16, v139
	v_and_b32_e32 v81, 0xffff0000, v139
	v_pk_mul_f32 v[80:81], v[122:123], v[80:81]
	v_and_b32_e32 v83, 0xffff0000, v140
	v_pk_fma_f32 v[80:81], v[114:115], v[84:85], v[80:81]
	s_waitcnt lgkmcnt(1)
	v_cndmask_b32_e64 v141, v104, v142, s[4:5]
	v_pk_fma_f32 v[80:81], v[110:111], v[82:83], v[80:81]
	v_cndmask_b32_e64 v142, v174, v137, s[6:7]
	v_pk_add_f32 v[80:81], v[118:119], v[80:81]
	v_lshlrev_b32_e32 v84, 16, v134
	v_mul_f32_e32 v82, 0xbfb8aa3b, v80
	v_mul_f32_e32 v83, 0xbfb8aa3b, v81
	v_exp_f32_e32 v82, v82
	v_exp_f32_e32 v83, v83
	v_and_b32_e32 v85, 0xffff0000, v134
	s_waitcnt lgkmcnt(0)
	v_cndmask_b32_e64 v143, v105, v143, s[4:5]
	v_add_f32_e32 v82, 1.0, v82
	v_add_f32_e32 v83, 1.0, v83
	v_rcp_f32_e32 v82, v82
	v_rcp_f32_e32 v83, v83
	v_or_b32_e32 v106, 32, v164
	v_pk_mul_f32 v[80:81], v[80:81], v[82:83]
	s_nop 0
	v_pk_mul_f32 v[78:79], v[78:79], v[80:81]
	v_lshlrev_b32_e32 v80, 16, v141
	v_and_b32_e32 v81, 0xffff0000, v141
	v_pk_mul_f32 v[80:81], v[100:101], v[80:81]
	v_lshlrev_b32_e32 v82, 16, v142
	v_and_b32_e32 v83, 0xffff0000, v142
	v_pk_fma_f32 v[80:81], v[92:93], v[84:85], v[80:81]
	v_lshlrev_b32_e32 v84, 16, v135
	v_pk_fma_f32 v[80:81], v[88:89], v[82:83], v[80:81]
	v_and_b32_e32 v85, 0xffff0000, v135
	v_pk_add_f32 v[80:81], v[96:97], v[80:81]
	s_nop 0
	v_mul_f32_e32 v82, 0xbfb8aa3b, v80
	v_mul_f32_e32 v83, 0xbfb8aa3b, v81
	v_exp_f32_e32 v82, v82
	v_exp_f32_e32 v83, v83
	v_add_f32_e32 v82, 1.0, v82
	v_add_f32_e32 v83, 1.0, v83
	v_rcp_f32_e32 v82, v82
	v_rcp_f32_e32 v83, v83
	s_nop 0
	v_pk_mul_f32 v[80:81], v[80:81], v[82:83]
	s_nop 0
	v_pk_mul_f32 v[80:81], v[72:73], v[80:81]
	v_lshlrev_b32_e32 v72, 16, v143
	v_and_b32_e32 v73, 0xffff0000, v143
	v_pk_mul_f32 v[72:73], v[102:103], v[72:73]
	v_lshlrev_b32_e32 v82, 16, v169
	v_and_b32_e32 v83, 0xffff0000, v169
	v_pk_fma_f32 v[72:73], v[94:95], v[84:85], v[72:73]
	v_cndmask_b32_e64 v84, v138, v165, s[6:7]
	v_pk_fma_f32 v[72:73], v[90:91], v[82:83], v[72:73]
	s_nop 0
	v_pk_add_f32 v[72:73], v[98:99], v[72:73]
	s_nop 0
	v_mul_f32_e32 v82, 0xbfb8aa3b, v72
	v_mul_f32_e32 v83, 0xbfb8aa3b, v73
	v_exp_f32_e32 v82, v82
	v_exp_f32_e32 v83, v83
	v_add_f32_e32 v82, 1.0, v82
	v_add_f32_e32 v83, 1.0, v83
	v_rcp_f32_e32 v82, v82
	v_rcp_f32_e32 v83, v83
	s_nop 0
	v_pk_mul_f32 v[72:73], v[72:73], v[82:83]
	s_nop 0
	v_pk_mul_f32 v[82:83], v[74:75], v[72:73]
	v_cvt_pk_bf16_f32 v72, v76, v77
	v_mad_i64_i32 v[76:77], s[0:1], v106, s26, v[172:173]
	v_cvt_pk_bf16_f32 v73, v78, v79
	v_cvt_pk_bf16_f32 v74, v80, v81
	v_cvt_pk_bf16_f32 v75, v82, v83
	v_lshl_add_u64 v[132:133], v[76:77], 0, v[204:205]
	global_store_dwordx4 v[132:133], v[72:75], off
	ds_bpermute_b32 v72, v193, v128
	ds_bpermute_b32 v73, v193, v129
	ds_bpermute_b32 v74, v193, v130
	ds_bpermute_b32 v75, v193, v131
	v_cndmask_b32_e64 v77, v107, v168, s[6:7]
	s_waitcnt lgkmcnt(3)
	v_cndmask_b32_e64 v76, v72, v86, s[4:5]
	s_waitcnt lgkmcnt(2)
	v_cndmask_b32_e64 v79, v73, v87, s[4:5]
	v_lshlrev_b32_e32 v72, 16, v76
	v_and_b32_e32 v73, 0xffff0000, v76
	s_waitcnt lgkmcnt(1)
	v_cndmask_b32_e64 v81, v74, v104, s[4:5]
	s_waitcnt lgkmcnt(0)
	v_cndmask_b32_e64 v83, v75, v105, s[4:5]
	v_lshlrev_b32_e32 v74, 16, v77
	v_and_b32_e32 v75, 0xffff0000, v77
	v_pk_mul_f32 v[72:73], v[120:121], v[72:73]
	v_lshlrev_b32_e32 v76, 16, v128
	v_and_b32_e32 v77, 0xffff0000, v128
	v_pk_fma_f32 v[72:73], v[112:113], v[76:77], v[72:73]
	v_cndmask_b32_e64 v80, v136, v167, s[6:7]
	v_pk_fma_f32 v[72:73], v[108:109], v[74:75], v[72:73]
	v_lshlrev_b32_e32 v76, 16, v129
	v_pk_add_f32 v[72:73], v[116:117], v[72:73]
	v_and_b32_e32 v77, 0xffff0000, v129
	v_mul_f32_e32 v74, 0xbfb8aa3b, v72
	v_mul_f32_e32 v75, 0xbfb8aa3b, v73
	v_exp_f32_e32 v74, v74
	v_exp_f32_e32 v75, v75
	v_cndmask_b32_e64 v82, v137, v166, s[6:7]
	v_or_b32_e32 v78, 48, v164
	v_add_f32_e32 v74, 1.0, v74
	v_add_f32_e32 v75, 1.0, v75
	v_rcp_f32_e32 v74, v74
	v_rcp_f32_e32 v75, v75
	s_nop 0
	v_pk_mul_f32 v[72:73], v[72:73], v[74:75]
	s_nop 0
	v_pk_mul_f32 v[68:69], v[68:69], v[72:73]
	v_lshlrev_b32_e32 v72, 16, v79
	v_and_b32_e32 v73, 0xffff0000, v79
	v_pk_mul_f32 v[72:73], v[122:123], v[72:73]
	v_lshlrev_b32_e32 v74, 16, v80
	v_and_b32_e32 v75, 0xffff0000, v80
	v_pk_fma_f32 v[72:73], v[114:115], v[76:77], v[72:73]
	v_lshlrev_b32_e32 v76, 16, v130
	v_pk_fma_f32 v[72:73], v[110:111], v[74:75], v[72:73]
	v_and_b32_e32 v77, 0xffff0000, v130
	v_pk_add_f32 v[72:73], v[118:119], v[72:73]
	s_nop 0
	v_mul_f32_e32 v74, 0xbfb8aa3b, v72
	v_mul_f32_e32 v75, 0xbfb8aa3b, v73
	v_exp_f32_e32 v74, v74
	v_exp_f32_e32 v75, v75
	v_add_f32_e32 v74, 1.0, v74
	v_add_f32_e32 v75, 1.0, v75
	v_rcp_f32_e32 v74, v74
	v_rcp_f32_e32 v75, v75
	s_nop 0
	v_pk_mul_f32 v[72:73], v[72:73], v[74:75]
	s_nop 0
	v_pk_mul_f32 v[70:71], v[70:71], v[72:73]
	v_lshlrev_b32_e32 v72, 16, v81
	v_and_b32_e32 v73, 0xffff0000, v81
	v_pk_mul_f32 v[72:73], v[100:101], v[72:73]
	v_lshlrev_b32_e32 v74, 16, v82
	v_and_b32_e32 v75, 0xffff0000, v82
	v_pk_fma_f32 v[72:73], v[92:93], v[76:77], v[72:73]
	v_lshlrev_b32_e32 v76, 16, v131
	v_pk_fma_f32 v[72:73], v[88:89], v[74:75], v[72:73]
	v_and_b32_e32 v77, 0xffff0000, v131
	v_pk_add_f32 v[72:73], v[96:97], v[72:73]
	s_nop 0
	v_mul_f32_e32 v74, 0xbfb8aa3b, v72
	v_mul_f32_e32 v75, 0xbfb8aa3b, v73
	v_exp_f32_e32 v74, v74
	v_exp_f32_e32 v75, v75
	v_add_f32_e32 v74, 1.0, v74
	v_add_f32_e32 v75, 1.0, v75
	v_rcp_f32_e32 v74, v74
	v_rcp_f32_e32 v75, v75
	s_nop 0
	v_pk_mul_f32 v[72:73], v[72:73], v[74:75]
	s_nop 0
	v_pk_mul_f32 v[72:73], v[64:65], v[72:73]
	v_lshlrev_b32_e32 v64, 16, v83
	v_and_b32_e32 v65, 0xffff0000, v83
	v_pk_mul_f32 v[64:65], v[102:103], v[64:65]
	v_lshlrev_b32_e32 v74, 16, v84
	v_and_b32_e32 v75, 0xffff0000, v84
	v_pk_fma_f32 v[64:65], v[94:95], v[76:77], v[64:65]
	s_nop 0
	v_pk_fma_f32 v[64:65], v[90:91], v[74:75], v[64:65]
	s_nop 0
	v_pk_add_f32 v[64:65], v[98:99], v[64:65]
	s_nop 0
	v_mul_f32_e32 v74, 0xbfb8aa3b, v64
	v_mul_f32_e32 v75, 0xbfb8aa3b, v65
	v_exp_f32_e32 v74, v74
	v_exp_f32_e32 v75, v75
	v_add_f32_e32 v74, 1.0, v74
	v_add_f32_e32 v75, 1.0, v75
	v_rcp_f32_e32 v74, v74
	v_rcp_f32_e32 v75, v75
	s_nop 0
	v_pk_mul_f32 v[64:65], v[64:65], v[74:75]
	s_nop 0
	v_pk_mul_f32 v[74:75], v[66:67], v[64:65]
	v_cvt_pk_bf16_f32 v64, v68, v69
	v_mad_i64_i32 v[68:69], s[0:1], v78, s26, v[172:173]
	v_cvt_pk_bf16_f32 v65, v70, v71
	v_cvt_pk_bf16_f32 v66, v72, v73
	v_cvt_pk_bf16_f32 v67, v74, v75
	v_lshl_add_u64 v[112:113], v[68:69], 0, v[204:205]
	global_store_dwordx4 v[112:113], v[64:67], off
	s_mov_b64 s[0:1], -1
	s_nop 0
	v_or_b32_e32 v64, 0x80, v192
	v_ashrrev_i32_e32 v65, 31, v64
	v_lshlrev_b64 v[64:65], 2, v[64:65]
	v_lshl_add_u64 v[66:67], s[46:47], 0, v[64:65]
	v_lshl_add_u64 v[72:73], s[48:49], 0, v[64:65]
	global_load_dwordx4 v[76:79], v[190:191], off offset:528
	global_load_dwordx4 v[92:95], v[190:191], off offset:512
	global_load_dwordx4 v[68:71], v[66:67], off offset:16
	global_load_dwordx4 v[84:87], v[66:67], off
	s_nop 0
	global_load_dwordx4 v[64:67], v[72:73], off offset:16
	global_load_dwordx4 v[80:83], v[72:73], off
	s_nop 0
	global_load_dwordx4 v[72:75], v[188:189], off offset:528
	global_load_dwordx4 v[88:91], v[188:189], off offset:512
	global_load_dwordx4 v[108:111], v[194:195], off offset:256
	global_load_dwordx4 v[104:107], v[198:199], off offset:256
	global_load_dwordx4 v[100:103], v[200:201], off offset:256
	global_load_dwordx4 v[96:99], v[206:207], off offset:256
	global_load_dwordx4 v[114:117], v[196:197], off offset:256
	global_load_dwordx4 v[118:121], v[202:203], off offset:256
	s_waitcnt vmcnt(5)
	ds_bpermute_b32 v130, v193, v108
	s_waitcnt vmcnt(4)
	ds_bpermute_b32 v136, v225, v104
	ds_bpermute_b32 v137, v225, v105
	ds_bpermute_b32 v134, v193, v110
	s_waitcnt vmcnt(1)
	v_cndmask_b32_e64 v122, v117, 0, s[62:63]
	v_cndmask_b32_e64 v123, v116, 0, s[62:63]
	s_waitcnt vmcnt(0)
	v_cndmask_b32_e64 v116, v119, 0, s[50:51]
	v_cndmask_b32_e64 v117, v118, 0, s[50:51]
	ds_bpermute_b32 v118, v225, v108
	ds_bpermute_b32 v119, v225, v109
	ds_bpermute_b32 v135, v193, v111
	v_cndmask_b32_e64 v128, v115, 0, s[62:63]
	v_cndmask_b32_e64 v129, v114, 0, s[62:63]
	v_cndmask_b32_e64 v114, v121, 0, s[50:51]
	v_cndmask_b32_e64 v115, v120, 0, s[50:51]
	ds_bpermute_b32 v120, v225, v110
	ds_bpermute_b32 v121, v225, v111
	ds_bpermute_b32 v138, v225, v106
	ds_bpermute_b32 v139, v225, v107
	s_waitcnt lgkmcnt(10)
	v_cndmask_b32_e64 v129, v130, v129, s[4:5]
	s_waitcnt lgkmcnt(6)
	v_cndmask_b32_e64 v140, v118, v136, s[6:7]
	s_waitcnt lgkmcnt(5)
	v_cndmask_b32_e64 v141, v119, v137, s[6:7]
	v_lshlrev_b32_e32 v118, 16, v129
	v_and_b32_e32 v119, 0xffff0000, v129
	v_cndmask_b32_e64 v142, v134, v123, s[4:5]
	s_waitcnt lgkmcnt(4)
	v_cndmask_b32_e64 v164, v135, v122, s[4:5]
	v_pk_mul_f32 v[118:119], v[92:93], v[118:119]
	v_lshlrev_b32_e32 v122, 16, v108
	v_and_b32_e32 v123, 0xffff0000, v108
	s_waitcnt lgkmcnt(1)
	v_cndmask_b32_e64 v143, v120, v138, s[6:7]
	s_waitcnt lgkmcnt(0)
	v_cndmask_b32_e64 v165, v121, v139, s[6:7]
	v_lshlrev_b32_e32 v120, 16, v140
	v_and_b32_e32 v121, 0xffff0000, v140
	v_pk_fma_f32 v[118:119], v[84:85], v[122:123], v[118:119]
	ds_bpermute_b32 v131, v193, v109
	v_pk_fma_f32 v[118:119], v[80:81], v[120:121], v[118:119]
	s_waitcnt lgkmcnt(0)
	v_cndmask_b32_e64 v128, v131, v128, s[4:5]
	v_pk_add_f32 v[118:119], v[88:89], v[118:119]
	s_nop 0
	v_mul_f32_e32 v108, 0xbfb8aa3b, v118
	v_exp_f32_e32 v108, v108
	s_nop 0
	v_add_f32_e32 v108, 1.0, v108
	v_rcp_f32_e32 v120, v108
	v_mul_f32_e32 v108, 0xbfb8aa3b, v119
	v_exp_f32_e32 v108, v108
	s_nop 0
	v_add_f32_e32 v108, 1.0, v108
	v_rcp_f32_e32 v121, v108
	v_lshlrev_b32_e32 v108, 16, v109
	v_and_b32_e32 v109, 0xffff0000, v109
	v_pk_mul_f32 v[118:119], v[118:119], v[120:121]
	s_nop 0
	v_pk_mul_f32 v[60:61], v[60:61], v[118:119]
	v_lshlrev_b32_e32 v118, 16, v128
	v_and_b32_e32 v119, 0xffff0000, v128
	v_pk_mul_f32 v[118:119], v[94:95], v[118:119]
	v_lshlrev_b32_e32 v120, 16, v141
	v_and_b32_e32 v121, 0xffff0000, v141
	v_pk_fma_f32 v[108:109], v[86:87], v[108:109], v[118:119]
	s_nop 0
	v_pk_fma_f32 v[108:109], v[82:83], v[120:121], v[108:109]
	v_lshlrev_b32_e32 v120, 16, v110
	v_pk_add_f32 v[108:109], v[90:91], v[108:109]
	v_and_b32_e32 v121, 0xffff0000, v110
	v_mul_f32_e32 v118, 0xbfb8aa3b, v108
	v_mul_f32_e32 v119, 0xbfb8aa3b, v109
	v_exp_f32_e32 v118, v118
	v_exp_f32_e32 v119, v119
	v_add_f32_e32 v118, 1.0, v118
	v_add_f32_e32 v119, 1.0, v119
	v_rcp_f32_e32 v118, v118
	v_rcp_f32_e32 v119, v119
	s_nop 0
	v_pk_mul_f32 v[108:109], v[108:109], v[118:119]
	s_nop 0
	v_pk_mul_f32 v[62:63], v[62:63], v[108:109]
	v_lshlrev_b32_e32 v108, 16, v142
	v_and_b32_e32 v109, 0xffff0000, v142
	v_pk_mul_f32 v[108:109], v[76:77], v[108:109]
	v_lshlrev_b32_e32 v118, 16, v143
	v_and_b32_e32 v119, 0xffff0000, v143
	v_pk_fma_f32 v[108:109], v[68:69], v[120:121], v[108:109]
	s_nop 0
	v_pk_fma_f32 v[108:109], v[64:65], v[118:119], v[108:109]
	s_nop 0
	v_pk_add_f32 v[108:109], v[72:73], v[108:109]
	s_nop 0
	v_mul_f32_e32 v110, 0xbfb8aa3b, v108
	v_exp_f32_e32 v110, v110
	s_nop 0
	v_add_f32_e32 v110, 1.0, v110
	v_rcp_f32_e32 v118, v110
	v_mul_f32_e32 v110, 0xbfb8aa3b, v109
	v_exp_f32_e32 v110, v110
	s_nop 0
	v_add_f32_e32 v110, 1.0, v110
	v_rcp_f32_e32 v119, v110
	v_lshlrev_b32_e32 v110, 16, v111
	v_and_b32_e32 v111, 0xffff0000, v111
	v_pk_mul_f32 v[108:109], v[108:109], v[118:119]
	s_nop 0
	v_pk_mul_f32 v[108:109], v[56:57], v[108:109]
	v_lshlrev_b32_e32 v56, 16, v164
	v_and_b32_e32 v57, 0xffff0000, v164
	v_pk_mul_f32 v[56:57], v[78:79], v[56:57]
	v_lshlrev_b32_e32 v118, 16, v165
	v_and_b32_e32 v119, 0xffff0000, v165
	v_pk_fma_f32 v[56:57], v[70:71], v[110:111], v[56:57]
	s_nop 0
	v_pk_fma_f32 v[56:57], v[66:67], v[118:119], v[56:57]
	ds_bpermute_b32 v118, v225, v102
	v_pk_add_f32 v[56:57], v[74:75], v[56:57]
	ds_bpermute_b32 v119, v225, v103
	v_mul_f32_e32 v110, 0xbfb8aa3b, v56
	v_mul_f32_e32 v111, 0xbfb8aa3b, v57
	v_exp_f32_e32 v110, v110
	v_exp_f32_e32 v111, v111
	s_waitcnt lgkmcnt(1)
	v_cndmask_b32_e64 v123, v138, v118, s[6:7]
	s_waitcnt lgkmcnt(0)
	v_cndmask_b32_e64 v129, v139, v119, s[6:7]
	v_add_f32_e32 v110, 1.0, v110
	v_add_f32_e32 v111, 1.0, v111
	v_rcp_f32_e32 v110, v110
	v_rcp_f32_e32 v111, v111
	s_nop 0
	v_pk_mul_f32 v[56:57], v[56:57], v[110:111]
	s_nop 0
	v_pk_mul_f32 v[110:111], v[58:59], v[56:57]
	v_cvt_pk_bf16_f32 v57, v62, v63
	ds_bpermute_b32 v62, v193, v104
	v_cvt_pk_bf16_f32 v59, v110, v111
	ds_bpermute_b32 v110, v225, v100
	v_cvt_pk_bf16_f32 v56, v60, v61
	v_cvt_pk_bf16_f32 v58, v108, v109
	global_store_dwordx4 v[156:157], v[56:59], off offset:256
	v_lshlrev_b32_e32 v60, 16, v104
	v_and_b32_e32 v61, 0xffff0000, v104
	s_waitcnt lgkmcnt(1)
	v_cndmask_b32_e64 v57, v62, v130, s[4:5]
	v_lshlrev_b32_e32 v56, 16, v57
	v_and_b32_e32 v57, 0xffff0000, v57
	s_waitcnt lgkmcnt(0)
	v_cndmask_b32_e64 v59, v136, v110, s[6:7]
	v_pk_mul_f32 v[56:57], v[92:93], v[56:57]
	v_lshlrev_b32_e32 v58, 16, v59
	v_and_b32_e32 v59, 0xffff0000, v59
	v_pk_fma_f32 v[56:57], v[84:85], v[60:61], v[56:57]
	ds_bpermute_b32 v63, v193, v105
	v_pk_fma_f32 v[56:57], v[80:81], v[58:59], v[56:57]
	ds_bpermute_b32 v111, v225, v101
	v_pk_add_f32 v[56:57], v[88:89], v[56:57]
	v_lshlrev_b32_e32 v60, 16, v105
	v_mul_f32_e32 v58, 0xbfb8aa3b, v56
	v_mul_f32_e32 v59, 0xbfb8aa3b, v57
	v_exp_f32_e32 v58, v58
	v_exp_f32_e32 v59, v59
	s_waitcnt lgkmcnt(1)
	v_cndmask_b32_e64 v120, v63, v131, s[4:5]
	s_waitcnt lgkmcnt(0)
	v_cndmask_b32_e64 v121, v137, v111, s[6:7]
	v_add_f32_e32 v58, 1.0, v58
	v_add_f32_e32 v59, 1.0, v59
	v_rcp_f32_e32 v58, v58
	v_rcp_f32_e32 v59, v59
	v_and_b32_e32 v61, 0xffff0000, v105
	ds_bpermute_b32 v108, v193, v106
	ds_bpermute_b32 v109, v193, v107
	v_pk_mul_f32 v[56:57], v[56:57], v[58:59]
	v_lshlrev_b32_e32 v58, 16, v121
	v_pk_mul_f32 v[52:53], v[52:53], v[56:57]
	v_lshlrev_b32_e32 v56, 16, v120
	v_and_b32_e32 v57, 0xffff0000, v120
	v_pk_mul_f32 v[56:57], v[94:95], v[56:57]
	v_and_b32_e32 v59, 0xffff0000, v121
	v_pk_fma_f32 v[56:57], v[86:87], v[60:61], v[56:57]
	s_waitcnt lgkmcnt(1)
	v_cndmask_b32_e64 v122, v108, v134, s[4:5]
	v_pk_fma_f32 v[56:57], v[82:83], v[58:59], v[56:57]
	v_lshlrev_b32_e32 v60, 16, v106
	v_pk_add_f32 v[56:57], v[90:91], v[56:57]
	v_and_b32_e32 v61, 0xffff0000, v106
	v_mul_f32_e32 v58, 0xbfb8aa3b, v56
	v_mul_f32_e32 v59, 0xbfb8aa3b, v57
	v_exp_f32_e32 v58, v58
	v_exp_f32_e32 v59, v59
	s_waitcnt lgkmcnt(0)
	v_cndmask_b32_e64 v128, v109, v135, s[4:5]
	v_add_f32_e32 v58, 1.0, v58
	v_add_f32_e32 v59, 1.0, v59
	v_rcp_f32_e32 v58, v58
	v_rcp_f32_e32 v59, v59
	s_nop 0
	v_pk_mul_f32 v[56:57], v[56:57], v[58:59]
	s_nop 0
	v_pk_mul_f32 v[54:55], v[54:55], v[56:57]
	v_lshlrev_b32_e32 v56, 16, v122
	v_and_b32_e32 v57, 0xffff0000, v122
	v_pk_mul_f32 v[56:57], v[76:77], v[56:57]
	v_lshlrev_b32_e32 v58, 16, v123
	v_and_b32_e32 v59, 0xffff0000, v123
	v_pk_fma_f32 v[56:57], v[68:69], v[60:61], v[56:57]
	v_lshlrev_b32_e32 v60, 16, v107
	v_pk_fma_f32 v[56:57], v[64:65], v[58:59], v[56:57]
	v_and_b32_e32 v61, 0xffff0000, v107
	v_pk_add_f32 v[56:57], v[72:73], v[56:57]
	s_nop 0
	v_mul_f32_e32 v58, 0xbfb8aa3b, v56
	v_mul_f32_e32 v59, 0xbfb8aa3b, v57
	v_exp_f32_e32 v58, v58
	v_exp_f32_e32 v59, v59
	v_add_f32_e32 v58, 1.0, v58
	v_add_f32_e32 v59, 1.0, v59
	v_rcp_f32_e32 v58, v58
	v_rcp_f32_e32 v59, v59
	s_nop 0
	v_pk_mul_f32 v[56:57], v[56:57], v[58:59]
	s_nop 0
	v_pk_mul_f32 v[56:57], v[48:49], v[56:57]
	v_lshlrev_b32_e32 v48, 16, v128
	v_and_b32_e32 v49, 0xffff0000, v128
	v_pk_mul_f32 v[48:49], v[78:79], v[48:49]
	v_lshlrev_b32_e32 v58, 16, v129
	v_and_b32_e32 v59, 0xffff0000, v129
	v_pk_fma_f32 v[48:49], v[70:71], v[60:61], v[48:49]
	ds_bpermute_b32 v60, v225, v98
	v_pk_fma_f32 v[48:49], v[66:67], v[58:59], v[48:49]
	ds_bpermute_b32 v61, v225, v99
	v_pk_add_f32 v[48:49], v[74:75], v[48:49]
	s_waitcnt lgkmcnt(1)
	v_cndmask_b32_e64 v105, v118, v60, s[6:7]
	v_mul_f32_e32 v58, 0xbfb8aa3b, v48
	v_mul_f32_e32 v59, 0xbfb8aa3b, v49
	v_exp_f32_e32 v58, v58
	v_exp_f32_e32 v59, v59
	s_waitcnt lgkmcnt(0)
	v_cndmask_b32_e64 v107, v119, v61, s[6:7]
	v_add_f32_e32 v58, 1.0, v58
	v_add_f32_e32 v59, 1.0, v59
	v_rcp_f32_e32 v58, v58
	v_rcp_f32_e32 v59, v59
	s_nop 0
	v_pk_mul_f32 v[48:49], v[48:49], v[58:59]
	s_nop 0
	v_pk_mul_f32 v[58:59], v[50:51], v[48:49]
	v_cvt_pk_bf16_f32 v49, v54, v55
	ds_bpermute_b32 v54, v193, v100
	v_cvt_pk_bf16_f32 v51, v58, v59
	ds_bpermute_b32 v58, v225, v96
	v_cvt_pk_bf16_f32 v48, v52, v53
	v_cvt_pk_bf16_f32 v50, v56, v57
	global_store_dwordx4 v[146:147], v[48:51], off offset:256
	v_lshlrev_b32_e32 v52, 16, v100
	v_and_b32_e32 v53, 0xffff0000, v100
	s_waitcnt lgkmcnt(1)
	v_cndmask_b32_e64 v49, v54, v62, s[4:5]
	v_lshlrev_b32_e32 v48, 16, v49
	v_and_b32_e32 v49, 0xffff0000, v49
	s_waitcnt lgkmcnt(0)
	v_cndmask_b32_e64 v51, v110, v58, s[6:7]
	v_pk_mul_f32 v[48:49], v[92:93], v[48:49]
	v_lshlrev_b32_e32 v50, 16, v51
	v_and_b32_e32 v51, 0xffff0000, v51
	v_pk_fma_f32 v[48:49], v[84:85], v[52:53], v[48:49]
	ds_bpermute_b32 v55, v193, v101
	v_pk_fma_f32 v[48:49], v[80:81], v[50:51], v[48:49]
	ds_bpermute_b32 v59, v225, v97
	v_pk_add_f32 v[48:49], v[88:89], v[48:49]
	v_lshlrev_b32_e32 v52, 16, v101
	v_mul_f32_e32 v50, 0xbfb8aa3b, v48
	v_mul_f32_e32 v51, 0xbfb8aa3b, v49
	v_exp_f32_e32 v50, v50
	v_exp_f32_e32 v51, v51
	s_waitcnt lgkmcnt(1)
	v_cndmask_b32_e64 v62, v55, v63, s[4:5]
	s_waitcnt lgkmcnt(0)
	v_cndmask_b32_e64 v63, v111, v59, s[6:7]
	v_add_f32_e32 v50, 1.0, v50
	v_add_f32_e32 v51, 1.0, v51
	v_rcp_f32_e32 v50, v50
	v_rcp_f32_e32 v51, v51
	v_and_b32_e32 v53, 0xffff0000, v101
	ds_bpermute_b32 v56, v193, v102
	ds_bpermute_b32 v57, v193, v103
	v_pk_mul_f32 v[48:49], v[48:49], v[50:51]
	v_lshlrev_b32_e32 v50, 16, v63
	v_pk_mul_f32 v[44:45], v[44:45], v[48:49]
	v_lshlrev_b32_e32 v48, 16, v62
	v_and_b32_e32 v49, 0xffff0000, v62
	v_pk_mul_f32 v[48:49], v[94:95], v[48:49]
	v_and_b32_e32 v51, 0xffff0000, v63
	v_pk_fma_f32 v[48:49], v[86:87], v[52:53], v[48:49]
	s_waitcnt lgkmcnt(1)
	v_cndmask_b32_e64 v104, v56, v108, s[4:5]
	v_pk_fma_f32 v[48:49], v[82:83], v[50:51], v[48:49]
	v_lshlrev_b32_e32 v52, 16, v102
	v_pk_add_f32 v[48:49], v[90:91], v[48:49]
	v_and_b32_e32 v53, 0xffff0000, v102
	v_mul_f32_e32 v50, 0xbfb8aa3b, v48
	v_mul_f32_e32 v51, 0xbfb8aa3b, v49
	v_exp_f32_e32 v50, v50
	v_exp_f32_e32 v51, v51
	s_waitcnt lgkmcnt(0)
	v_cndmask_b32_e64 v106, v57, v109, s[4:5]
	v_add_f32_e32 v50, 1.0, v50
	v_add_f32_e32 v51, 1.0, v51
	v_rcp_f32_e32 v50, v50
	v_rcp_f32_e32 v51, v51
	s_nop 0
	v_pk_mul_f32 v[48:49], v[48:49], v[50:51]
	s_nop 0
	v_pk_mul_f32 v[46:47], v[46:47], v[48:49]
	v_lshlrev_b32_e32 v48, 16, v104
	v_and_b32_e32 v49, 0xffff0000, v104
	v_pk_mul_f32 v[48:49], v[76:77], v[48:49]
	v_lshlrev_b32_e32 v50, 16, v105
	v_and_b32_e32 v51, 0xffff0000, v105
	v_pk_fma_f32 v[48:49], v[68:69], v[52:53], v[48:49]
	v_lshlrev_b32_e32 v52, 16, v103
	v_pk_fma_f32 v[48:49], v[64:65], v[50:51], v[48:49]
	v_and_b32_e32 v53, 0xffff0000, v103
	v_pk_add_f32 v[48:49], v[72:73], v[48:49]
	s_nop 0
	v_mul_f32_e32 v50, 0xbfb8aa3b, v48
	v_mul_f32_e32 v51, 0xbfb8aa3b, v49
	v_exp_f32_e32 v50, v50
	v_exp_f32_e32 v51, v51
	v_add_f32_e32 v50, 1.0, v50
	v_add_f32_e32 v51, 1.0, v51
	v_rcp_f32_e32 v50, v50
	v_rcp_f32_e32 v51, v51
	s_nop 0
	v_pk_mul_f32 v[48:49], v[48:49], v[50:51]
	s_nop 0
	v_pk_mul_f32 v[48:49], v[40:41], v[48:49]
	v_lshlrev_b32_e32 v40, 16, v106
	v_and_b32_e32 v41, 0xffff0000, v106
	v_pk_mul_f32 v[40:41], v[78:79], v[40:41]
	v_lshlrev_b32_e32 v50, 16, v107
	v_and_b32_e32 v51, 0xffff0000, v107
	v_pk_fma_f32 v[40:41], v[70:71], v[52:53], v[40:41]
	s_nop 0
	v_pk_fma_f32 v[40:41], v[66:67], v[50:51], v[40:41]
	s_nop 0
	v_pk_add_f32 v[40:41], v[74:75], v[40:41]
	s_nop 0
	v_mul_f32_e32 v50, 0xbfb8aa3b, v40
	v_mul_f32_e32 v51, 0xbfb8aa3b, v41
	v_exp_f32_e32 v50, v50
	v_exp_f32_e32 v51, v51
	v_add_f32_e32 v50, 1.0, v50
	v_add_f32_e32 v51, 1.0, v51
	v_rcp_f32_e32 v50, v50
	v_rcp_f32_e32 v51, v51
	s_nop 0
	v_pk_mul_f32 v[40:41], v[40:41], v[50:51]
	s_nop 0
	v_pk_mul_f32 v[50:51], v[42:43], v[40:41]
	v_cvt_pk_bf16_f32 v40, v44, v45
	v_cvt_pk_bf16_f32 v41, v46, v47
	v_cvt_pk_bf16_f32 v42, v48, v49
	v_cvt_pk_bf16_f32 v43, v50, v51
	global_store_dwordx4 v[148:149], v[40:43], off offset:256
	ds_bpermute_b32 v40, v193, v96
	ds_bpermute_b32 v41, v193, v97
	ds_bpermute_b32 v42, v193, v98
	ds_bpermute_b32 v43, v193, v99
	v_cndmask_b32_e64 v45, v58, v117, s[6:7]
	s_waitcnt lgkmcnt(3)
	v_cndmask_b32_e64 v44, v40, v54, s[4:5]
	s_waitcnt lgkmcnt(2)
	v_cndmask_b32_e64 v46, v41, v55, s[4:5]
	v_lshlrev_b32_e32 v40, 16, v44
	v_and_b32_e32 v41, 0xffff0000, v44
	s_waitcnt lgkmcnt(1)
	v_cndmask_b32_e64 v48, v42, v56, s[4:5]
	s_waitcnt lgkmcnt(0)
	v_cndmask_b32_e64 v50, v43, v57, s[4:5]
	v_lshlrev_b32_e32 v42, 16, v45
	v_and_b32_e32 v43, 0xffff0000, v45
	v_pk_mul_f32 v[40:41], v[92:93], v[40:41]
	v_lshlrev_b32_e32 v44, 16, v96
	v_and_b32_e32 v45, 0xffff0000, v96
	v_pk_fma_f32 v[40:41], v[84:85], v[44:45], v[40:41]
	v_cndmask_b32_e64 v47, v59, v116, s[6:7]
	v_pk_fma_f32 v[40:41], v[80:81], v[42:43], v[40:41]
	v_lshlrev_b32_e32 v44, 16, v97
	v_pk_add_f32 v[40:41], v[88:89], v[40:41]
	v_and_b32_e32 v45, 0xffff0000, v97
	v_mul_f32_e32 v42, 0xbfb8aa3b, v40
	v_mul_f32_e32 v43, 0xbfb8aa3b, v41
	v_exp_f32_e32 v42, v42
	v_exp_f32_e32 v43, v43
	v_cndmask_b32_e64 v49, v60, v115, s[6:7]
	v_cndmask_b32_e64 v51, v61, v114, s[6:7]
	v_add_f32_e32 v42, 1.0, v42
	v_add_f32_e32 v43, 1.0, v43
	v_rcp_f32_e32 v42, v42
	v_rcp_f32_e32 v43, v43
	s_nop 0
	v_pk_mul_f32 v[40:41], v[40:41], v[42:43]
	s_nop 0
	v_pk_mul_f32 v[36:37], v[36:37], v[40:41]
	v_lshlrev_b32_e32 v40, 16, v46
	v_and_b32_e32 v41, 0xffff0000, v46
	v_pk_mul_f32 v[40:41], v[94:95], v[40:41]
	v_lshlrev_b32_e32 v42, 16, v47
	v_and_b32_e32 v43, 0xffff0000, v47
	v_pk_fma_f32 v[40:41], v[86:87], v[44:45], v[40:41]
	v_lshlrev_b32_e32 v44, 16, v98
	v_pk_fma_f32 v[40:41], v[82:83], v[42:43], v[40:41]
	v_and_b32_e32 v45, 0xffff0000, v98
	v_pk_add_f32 v[40:41], v[90:91], v[40:41]
	s_nop 0
	v_mul_f32_e32 v42, 0xbfb8aa3b, v40
	v_mul_f32_e32 v43, 0xbfb8aa3b, v41
	v_exp_f32_e32 v42, v42
	v_exp_f32_e32 v43, v43
	v_add_f32_e32 v42, 1.0, v42
	v_add_f32_e32 v43, 1.0, v43
	v_rcp_f32_e32 v42, v42
	v_rcp_f32_e32 v43, v43
	s_nop 0
	v_pk_mul_f32 v[40:41], v[40:41], v[42:43]
	s_nop 0
	v_pk_mul_f32 v[38:39], v[38:39], v[40:41]
	v_lshlrev_b32_e32 v40, 16, v48
	v_and_b32_e32 v41, 0xffff0000, v48
	v_pk_mul_f32 v[40:41], v[76:77], v[40:41]
	v_lshlrev_b32_e32 v42, 16, v49
	v_and_b32_e32 v43, 0xffff0000, v49
	v_pk_fma_f32 v[40:41], v[68:69], v[44:45], v[40:41]
	v_lshlrev_b32_e32 v44, 16, v99
	v_pk_fma_f32 v[40:41], v[64:65], v[42:43], v[40:41]
	v_and_b32_e32 v45, 0xffff0000, v99
	v_pk_add_f32 v[40:41], v[72:73], v[40:41]
	s_nop 0
	v_mul_f32_e32 v42, 0xbfb8aa3b, v40
	v_mul_f32_e32 v43, 0xbfb8aa3b, v41
	v_exp_f32_e32 v42, v42
	v_exp_f32_e32 v43, v43
	v_add_f32_e32 v42, 1.0, v42
	v_add_f32_e32 v43, 1.0, v43
	v_rcp_f32_e32 v42, v42
	v_rcp_f32_e32 v43, v43
	s_nop 0
	v_pk_mul_f32 v[40:41], v[40:41], v[42:43]
	s_nop 0
	v_pk_mul_f32 v[40:41], v[32:33], v[40:41]
	v_lshlrev_b32_e32 v32, 16, v50
	v_and_b32_e32 v33, 0xffff0000, v50
	v_pk_mul_f32 v[32:33], v[78:79], v[32:33]
	v_lshlrev_b32_e32 v42, 16, v51
	v_and_b32_e32 v43, 0xffff0000, v51
	v_pk_fma_f32 v[32:33], v[70:71], v[44:45], v[32:33]
	s_nop 0
	v_pk_fma_f32 v[32:33], v[66:67], v[42:43], v[32:33]
	s_nop 0
	v_pk_add_f32 v[32:33], v[74:75], v[32:33]
	s_nop 0
	v_mul_f32_e32 v42, 0xbfb8aa3b, v32
	v_mul_f32_e32 v43, 0xbfb8aa3b, v33
	v_exp_f32_e32 v42, v42
	v_exp_f32_e32 v43, v43
	v_add_f32_e32 v42, 1.0, v42
	v_add_f32_e32 v43, 1.0, v43
	v_rcp_f32_e32 v42, v42
	v_rcp_f32_e32 v43, v43
	s_nop 0
	v_pk_mul_f32 v[32:33], v[32:33], v[42:43]
	s_nop 0
	v_pk_mul_f32 v[42:43], v[34:35], v[32:33]
	v_cvt_pk_bf16_f32 v32, v36, v37
	v_cvt_pk_bf16_f32 v33, v38, v39
	v_cvt_pk_bf16_f32 v34, v40, v41
	v_cvt_pk_bf16_f32 v35, v42, v43
	global_store_dwordx4 v[144:145], v[32:35], off offset:256
	global_load_dwordx4 v[48:51], v[150:151], off offset:256
	global_load_dwordx4 v[44:47], v[152:153], off offset:256
	global_load_dwordx4 v[40:43], v[154:155], off offset:256
	global_load_dwordx4 v[32:35], v[158:159], off offset:256
	global_load_dwordx4 v[52:55], v[162:163], off offset:256
	global_load_dwordx4 v[36:39], v[160:161], off offset:256
	s_waitcnt vmcnt(5)
	ds_bpermute_b32 v58, v193, v48
	ds_bpermute_b32 v56, v225, v48
	ds_bpermute_b32 v59, v193, v49
	s_waitcnt vmcnt(4)
	ds_bpermute_b32 v96, v225, v44
	ds_bpermute_b32 v57, v225, v49
	ds_bpermute_b32 v60, v193, v50
	ds_bpermute_b32 v62, v193, v51
	ds_bpermute_b32 v97, v225, v45
	s_waitcnt vmcnt(1)
	v_cndmask_b32_e64 v52, v52, 0, s[22:23]
	v_cndmask_b32_e64 v53, v53, 0, s[22:23]
	s_waitcnt lgkmcnt(7)
	v_cndmask_b32_e64 v100, v58, v52, s[4:5]
	v_cndmask_b32_e64 v55, v55, 0, s[22:23]
	v_cndmask_b32_e64 v54, v54, 0, s[22:23]
	s_waitcnt lgkmcnt(4)
	v_cndmask_b32_e64 v56, v56, v96, s[6:7]
	v_cndmask_b32_e64 v101, v59, v53, s[4:5]
	v_lshlrev_b32_e32 v52, 16, v100
	v_and_b32_e32 v53, 0xffff0000, v100
	s_waitcnt lgkmcnt(0)
	v_cndmask_b32_e64 v102, v57, v97, s[6:7]
	v_cndmask_b32_e64 v103, v60, v54, s[4:5]
	v_cndmask_b32_e64 v104, v62, v55, s[4:5]
	v_lshlrev_b32_e32 v54, 16, v56
	v_and_b32_e32 v55, 0xffff0000, v56
	v_pk_mul_f32 v[52:53], v[92:93], v[52:53]
	v_lshlrev_b32_e32 v56, 16, v48
	v_and_b32_e32 v57, 0xffff0000, v48
	v_pk_fma_f32 v[52:53], v[84:85], v[56:57], v[52:53]
	ds_bpermute_b32 v61, v225, v50
	v_pk_fma_f32 v[52:53], v[80:81], v[54:55], v[52:53]
	ds_bpermute_b32 v98, v225, v46
	v_pk_add_f32 v[52:53], v[88:89], v[52:53]
	ds_bpermute_b32 v63, v225, v51
	v_mul_f32_e32 v48, 0xbfb8aa3b, v52
	v_exp_f32_e32 v48, v48
	s_waitcnt lgkmcnt(1)
	v_cndmask_b32_e64 v61, v61, v98, s[6:7]
	ds_bpermute_b32 v99, v225, v47
	v_add_f32_e32 v48, 1.0, v48
	v_rcp_f32_e32 v54, v48
	v_mul_f32_e32 v48, 0xbfb8aa3b, v53
	v_exp_f32_e32 v48, v48
	s_waitcnt lgkmcnt(0)
	v_cndmask_b32_e64 v63, v63, v99, s[6:7]
	v_add_f32_e32 v48, 1.0, v48
	v_rcp_f32_e32 v55, v48
	v_lshlrev_b32_e32 v48, 16, v49
	v_and_b32_e32 v49, 0xffff0000, v49
	v_pk_mul_f32 v[52:53], v[52:53], v[54:55]
	s_nop 0
	v_pk_mul_f32 v[28:29], v[28:29], v[52:53]
	v_lshlrev_b32_e32 v52, 16, v101
	v_and_b32_e32 v53, 0xffff0000, v101
	v_pk_mul_f32 v[52:53], v[94:95], v[52:53]
	v_lshlrev_b32_e32 v54, 16, v102
	v_and_b32_e32 v55, 0xffff0000, v102
	v_pk_fma_f32 v[48:49], v[86:87], v[48:49], v[52:53]
	s_nop 0
	v_pk_fma_f32 v[48:49], v[82:83], v[54:55], v[48:49]
	v_lshlrev_b32_e32 v54, 16, v50
	v_pk_add_f32 v[48:49], v[90:91], v[48:49]
	v_and_b32_e32 v55, 0xffff0000, v50
	v_mul_f32_e32 v52, 0xbfb8aa3b, v48
	v_mul_f32_e32 v53, 0xbfb8aa3b, v49
	v_exp_f32_e32 v52, v52
	v_exp_f32_e32 v53, v53
	v_add_f32_e32 v52, 1.0, v52
	v_add_f32_e32 v53, 1.0, v53
	v_rcp_f32_e32 v52, v52
	v_rcp_f32_e32 v53, v53
	s_nop 0
	v_pk_mul_f32 v[48:49], v[48:49], v[52:53]
	s_nop 0
	v_pk_mul_f32 v[30:31], v[30:31], v[48:49]
	v_lshlrev_b32_e32 v48, 16, v103
	v_and_b32_e32 v49, 0xffff0000, v103
	v_pk_mul_f32 v[48:49], v[76:77], v[48:49]
	v_lshlrev_b32_e32 v52, 16, v61
	v_and_b32_e32 v53, 0xffff0000, v61
	v_pk_fma_f32 v[48:49], v[68:69], v[54:55], v[48:49]
	s_nop 0
	v_pk_fma_f32 v[48:49], v[64:65], v[52:53], v[48:49]
	s_nop 0
	v_pk_add_f32 v[48:49], v[72:73], v[48:49]
	s_nop 0
	v_mul_f32_e32 v50, 0xbfb8aa3b, v48
	v_exp_f32_e32 v50, v50
	s_nop 0
	v_add_f32_e32 v50, 1.0, v50
	v_rcp_f32_e32 v52, v50
	v_mul_f32_e32 v50, 0xbfb8aa3b, v49
	v_exp_f32_e32 v50, v50
	s_nop 0
	v_add_f32_e32 v50, 1.0, v50
	v_rcp_f32_e32 v53, v50
	v_lshlrev_b32_e32 v50, 16, v51
	v_and_b32_e32 v51, 0xffff0000, v51
	v_pk_mul_f32 v[48:49], v[48:49], v[52:53]
	s_nop 0
	v_pk_mul_f32 v[48:49], v[24:25], v[48:49]
	v_lshlrev_b32_e32 v24, 16, v104
	v_and_b32_e32 v25, 0xffff0000, v104
	v_pk_mul_f32 v[24:25], v[78:79], v[24:25]
	v_lshlrev_b32_e32 v52, 16, v63
	v_and_b32_e32 v53, 0xffff0000, v63
	v_pk_fma_f32 v[24:25], v[70:71], v[50:51], v[24:25]
	s_nop 0
	v_pk_fma_f32 v[24:25], v[66:67], v[52:53], v[24:25]
	ds_bpermute_b32 v52, v225, v42
	v_pk_add_f32 v[24:25], v[74:75], v[24:25]
	ds_bpermute_b32 v53, v225, v43
	v_mul_f32_e32 v50, 0xbfb8aa3b, v24
	v_mul_f32_e32 v51, 0xbfb8aa3b, v25
	v_exp_f32_e32 v50, v50
	v_exp_f32_e32 v51, v51
	s_waitcnt lgkmcnt(1)
	v_cndmask_b32_e64 v57, v98, v52, s[6:7]
	v_add_f32_e32 v50, 1.0, v50
	v_add_f32_e32 v51, 1.0, v51
	v_rcp_f32_e32 v50, v50
	v_rcp_f32_e32 v51, v51
	s_nop 0
	v_pk_mul_f32 v[24:25], v[24:25], v[50:51]
	s_nop 0
	v_pk_mul_f32 v[50:51], v[26:27], v[24:25]
	v_cvt_pk_bf16_f32 v25, v30, v31
	ds_bpermute_b32 v30, v193, v44
	v_cvt_pk_bf16_f32 v27, v50, v51
	ds_bpermute_b32 v50, v225, v40
	v_cvt_pk_bf16_f32 v24, v28, v29
	v_cvt_pk_bf16_f32 v26, v48, v49
	global_store_dwordx4 v[124:125], v[24:27], off offset:256
	v_lshlrev_b32_e32 v28, 16, v44
	v_and_b32_e32 v29, 0xffff0000, v44
	s_waitcnt lgkmcnt(1)
	v_cndmask_b32_e64 v25, v30, v58, s[4:5]
	v_lshlrev_b32_e32 v24, 16, v25
	v_and_b32_e32 v25, 0xffff0000, v25
	s_waitcnt lgkmcnt(0)
	v_cndmask_b32_e64 v27, v96, v50, s[6:7]
	v_pk_mul_f32 v[24:25], v[92:93], v[24:25]
	v_lshlrev_b32_e32 v26, 16, v27
	v_and_b32_e32 v27, 0xffff0000, v27
	v_pk_fma_f32 v[24:25], v[84:85], v[28:29], v[24:25]
	ds_bpermute_b32 v31, v193, v45
	v_pk_fma_f32 v[24:25], v[80:81], v[26:27], v[24:25]
	ds_bpermute_b32 v51, v225, v41
	v_pk_add_f32 v[24:25], v[88:89], v[24:25]
	v_lshlrev_b32_e32 v28, 16, v45
	v_mul_f32_e32 v26, 0xbfb8aa3b, v24
	v_mul_f32_e32 v27, 0xbfb8aa3b, v25
	v_exp_f32_e32 v26, v26
	v_exp_f32_e32 v27, v27
	s_waitcnt lgkmcnt(1)
	v_cndmask_b32_e64 v54, v31, v59, s[4:5]
	s_waitcnt lgkmcnt(0)
	v_cndmask_b32_e64 v55, v97, v51, s[6:7]
	v_add_f32_e32 v26, 1.0, v26
	v_add_f32_e32 v27, 1.0, v27
	v_rcp_f32_e32 v26, v26
	v_rcp_f32_e32 v27, v27
	v_and_b32_e32 v29, 0xffff0000, v45
	ds_bpermute_b32 v48, v193, v46
	ds_bpermute_b32 v49, v193, v47
	v_pk_mul_f32 v[24:25], v[24:25], v[26:27]
	v_lshlrev_b32_e32 v26, 16, v55
	v_pk_mul_f32 v[20:21], v[20:21], v[24:25]
	v_lshlrev_b32_e32 v24, 16, v54
	v_and_b32_e32 v25, 0xffff0000, v54
	v_pk_mul_f32 v[24:25], v[94:95], v[24:25]
	v_and_b32_e32 v27, 0xffff0000, v55
	v_pk_fma_f32 v[24:25], v[86:87], v[28:29], v[24:25]
	s_waitcnt lgkmcnt(1)
	v_cndmask_b32_e64 v56, v48, v60, s[4:5]
	v_pk_fma_f32 v[24:25], v[82:83], v[26:27], v[24:25]
	v_lshlrev_b32_e32 v28, 16, v46
	v_pk_add_f32 v[24:25], v[90:91], v[24:25]
	v_and_b32_e32 v29, 0xffff0000, v46
	v_mul_f32_e32 v26, 0xbfb8aa3b, v24
	v_mul_f32_e32 v27, 0xbfb8aa3b, v25
	v_exp_f32_e32 v26, v26
	v_exp_f32_e32 v27, v27
	s_waitcnt lgkmcnt(0)
	v_cndmask_b32_e64 v58, v49, v62, s[4:5]
	v_cndmask_b32_e64 v59, v99, v53, s[6:7]
	v_add_f32_e32 v26, 1.0, v26
	v_add_f32_e32 v27, 1.0, v27
	v_rcp_f32_e32 v26, v26
	v_rcp_f32_e32 v27, v27
	s_nop 0
	v_pk_mul_f32 v[24:25], v[24:25], v[26:27]
	s_nop 0
	v_pk_mul_f32 v[22:23], v[22:23], v[24:25]
	v_lshlrev_b32_e32 v24, 16, v56
	v_and_b32_e32 v25, 0xffff0000, v56
	v_pk_mul_f32 v[24:25], v[76:77], v[24:25]
	v_lshlrev_b32_e32 v26, 16, v57
	v_and_b32_e32 v27, 0xffff0000, v57
	v_pk_fma_f32 v[24:25], v[68:69], v[28:29], v[24:25]
	v_lshlrev_b32_e32 v28, 16, v47
	v_pk_fma_f32 v[24:25], v[64:65], v[26:27], v[24:25]
	v_and_b32_e32 v29, 0xffff0000, v47
	v_pk_add_f32 v[24:25], v[72:73], v[24:25]
	s_nop 0
	v_mul_f32_e32 v26, 0xbfb8aa3b, v24
	v_mul_f32_e32 v27, 0xbfb8aa3b, v25
	v_exp_f32_e32 v26, v26
	v_exp_f32_e32 v27, v27
	v_add_f32_e32 v26, 1.0, v26
	v_add_f32_e32 v27, 1.0, v27
	v_rcp_f32_e32 v26, v26
	v_rcp_f32_e32 v27, v27
	s_nop 0
	v_pk_mul_f32 v[24:25], v[24:25], v[26:27]
	s_nop 0
	v_pk_mul_f32 v[24:25], v[16:17], v[24:25]
	v_lshlrev_b32_e32 v16, 16, v58
	v_and_b32_e32 v17, 0xffff0000, v58
	v_pk_mul_f32 v[16:17], v[78:79], v[16:17]
	v_lshlrev_b32_e32 v26, 16, v59
	v_and_b32_e32 v27, 0xffff0000, v59
	v_pk_fma_f32 v[16:17], v[70:71], v[28:29], v[16:17]
	ds_bpermute_b32 v28, v225, v34
	v_pk_fma_f32 v[16:17], v[66:67], v[26:27], v[16:17]
	ds_bpermute_b32 v29, v225, v35
	v_pk_add_f32 v[16:17], v[74:75], v[16:17]
	s_waitcnt lgkmcnt(1)
	v_cndmask_b32_e64 v45, v52, v28, s[6:7]
	v_mul_f32_e32 v26, 0xbfb8aa3b, v16
	v_mul_f32_e32 v27, 0xbfb8aa3b, v17
	v_exp_f32_e32 v26, v26
	v_exp_f32_e32 v27, v27
	s_waitcnt lgkmcnt(0)
	v_cndmask_b32_e64 v47, v53, v29, s[6:7]
	v_add_f32_e32 v26, 1.0, v26
	v_add_f32_e32 v27, 1.0, v27
	v_rcp_f32_e32 v26, v26
	v_rcp_f32_e32 v27, v27
	s_nop 0
	v_pk_mul_f32 v[16:17], v[16:17], v[26:27]
	s_nop 0
	v_pk_mul_f32 v[26:27], v[18:19], v[16:17]
	v_cvt_pk_bf16_f32 v17, v22, v23
	ds_bpermute_b32 v22, v193, v40
	v_cvt_pk_bf16_f32 v19, v26, v27
	ds_bpermute_b32 v26, v225, v32
	v_cvt_pk_bf16_f32 v16, v20, v21
	v_cvt_pk_bf16_f32 v18, v24, v25
	global_store_dwordx4 v[126:127], v[16:19], off offset:256
	v_lshlrev_b32_e32 v20, 16, v40
	v_and_b32_e32 v21, 0xffff0000, v40
	s_waitcnt lgkmcnt(1)
	v_cndmask_b32_e64 v17, v22, v30, s[4:5]
	v_lshlrev_b32_e32 v16, 16, v17
	v_and_b32_e32 v17, 0xffff0000, v17
	s_waitcnt lgkmcnt(0)
	v_cndmask_b32_e64 v19, v50, v26, s[6:7]
	v_pk_mul_f32 v[16:17], v[92:93], v[16:17]
	v_lshlrev_b32_e32 v18, 16, v19
	v_and_b32_e32 v19, 0xffff0000, v19
	v_pk_fma_f32 v[16:17], v[84:85], v[20:21], v[16:17]
	ds_bpermute_b32 v23, v193, v41
	v_pk_fma_f32 v[16:17], v[80:81], v[18:19], v[16:17]
	ds_bpermute_b32 v27, v225, v33
	v_pk_add_f32 v[16:17], v[88:89], v[16:17]
	v_lshlrev_b32_e32 v20, 16, v41
	v_mul_f32_e32 v18, 0xbfb8aa3b, v16
	v_mul_f32_e32 v19, 0xbfb8aa3b, v17
	v_exp_f32_e32 v18, v18
	v_exp_f32_e32 v19, v19
	s_waitcnt lgkmcnt(1)
	v_cndmask_b32_e64 v30, v23, v31, s[4:5]
	s_waitcnt lgkmcnt(0)
	v_cndmask_b32_e64 v31, v51, v27, s[6:7]
	v_add_f32_e32 v18, 1.0, v18
	v_add_f32_e32 v19, 1.0, v19
	v_rcp_f32_e32 v18, v18
	v_rcp_f32_e32 v19, v19
	v_and_b32_e32 v21, 0xffff0000, v41
	ds_bpermute_b32 v24, v193, v42
	ds_bpermute_b32 v25, v193, v43
	v_pk_mul_f32 v[16:17], v[16:17], v[18:19]
	v_lshlrev_b32_e32 v18, 16, v31
	v_pk_mul_f32 v[12:13], v[12:13], v[16:17]
	v_lshlrev_b32_e32 v16, 16, v30
	v_and_b32_e32 v17, 0xffff0000, v30
	v_pk_mul_f32 v[16:17], v[94:95], v[16:17]
	v_and_b32_e32 v19, 0xffff0000, v31
	v_pk_fma_f32 v[16:17], v[86:87], v[20:21], v[16:17]
	s_waitcnt lgkmcnt(1)
	v_cndmask_b32_e64 v44, v24, v48, s[4:5]
	v_pk_fma_f32 v[16:17], v[82:83], v[18:19], v[16:17]
	v_lshlrev_b32_e32 v20, 16, v42
	v_pk_add_f32 v[16:17], v[90:91], v[16:17]
	v_and_b32_e32 v21, 0xffff0000, v42
	v_mul_f32_e32 v18, 0xbfb8aa3b, v16
	v_mul_f32_e32 v19, 0xbfb8aa3b, v17
	v_exp_f32_e32 v18, v18
	v_exp_f32_e32 v19, v19
	s_waitcnt lgkmcnt(0)
	v_cndmask_b32_e64 v46, v25, v49, s[4:5]
	v_add_f32_e32 v18, 1.0, v18
	v_add_f32_e32 v19, 1.0, v19
	v_rcp_f32_e32 v18, v18
	v_rcp_f32_e32 v19, v19
	s_nop 0
	v_pk_mul_f32 v[16:17], v[16:17], v[18:19]
	s_nop 0
	v_pk_mul_f32 v[14:15], v[14:15], v[16:17]
	v_lshlrev_b32_e32 v16, 16, v44
	v_and_b32_e32 v17, 0xffff0000, v44
	v_pk_mul_f32 v[16:17], v[76:77], v[16:17]
	v_lshlrev_b32_e32 v18, 16, v45
	v_and_b32_e32 v19, 0xffff0000, v45
	v_pk_fma_f32 v[16:17], v[68:69], v[20:21], v[16:17]
	v_lshlrev_b32_e32 v20, 16, v43
	v_pk_fma_f32 v[16:17], v[64:65], v[18:19], v[16:17]
	v_and_b32_e32 v21, 0xffff0000, v43
	v_pk_add_f32 v[16:17], v[72:73], v[16:17]
	s_nop 0
	v_mul_f32_e32 v18, 0xbfb8aa3b, v16
	v_mul_f32_e32 v19, 0xbfb8aa3b, v17
	v_exp_f32_e32 v18, v18
	v_exp_f32_e32 v19, v19
	v_add_f32_e32 v18, 1.0, v18
	v_add_f32_e32 v19, 1.0, v19
	v_rcp_f32_e32 v18, v18
	v_rcp_f32_e32 v19, v19
	s_nop 0
	v_pk_mul_f32 v[16:17], v[16:17], v[18:19]
	s_nop 0
	v_pk_mul_f32 v[16:17], v[8:9], v[16:17]
	v_lshlrev_b32_e32 v8, 16, v46
	v_and_b32_e32 v9, 0xffff0000, v46
	v_pk_mul_f32 v[8:9], v[78:79], v[8:9]
	v_lshlrev_b32_e32 v18, 16, v47
	v_and_b32_e32 v19, 0xffff0000, v47
	v_pk_fma_f32 v[8:9], v[70:71], v[20:21], v[8:9]
	s_nop 0
	v_pk_fma_f32 v[8:9], v[66:67], v[18:19], v[8:9]
	s_nop 0
	v_pk_add_f32 v[8:9], v[74:75], v[8:9]
	s_nop 0
	v_mul_f32_e32 v18, 0xbfb8aa3b, v8
	v_mul_f32_e32 v19, 0xbfb8aa3b, v9
	v_exp_f32_e32 v18, v18
	v_exp_f32_e32 v19, v19
	v_add_f32_e32 v18, 1.0, v18
	v_add_f32_e32 v19, 1.0, v19
	v_rcp_f32_e32 v18, v18
	v_rcp_f32_e32 v19, v19
	s_nop 0
	v_pk_mul_f32 v[8:9], v[8:9], v[18:19]
	s_nop 0
	v_pk_mul_f32 v[18:19], v[10:11], v[8:9]
	v_cvt_pk_bf16_f32 v8, v12, v13
	v_cvt_pk_bf16_f32 v9, v14, v15
	v_cvt_pk_bf16_f32 v10, v16, v17
	v_cvt_pk_bf16_f32 v11, v18, v19
	global_store_dwordx4 v[132:133], v[8:11], off offset:256
	ds_bpermute_b32 v8, v193, v32
	ds_bpermute_b32 v9, v193, v33
	ds_bpermute_b32 v10, v193, v34
	ds_bpermute_b32 v11, v193, v35
	s_waitcnt vmcnt(3)
	v_cndmask_b32_e64 v12, v39, 0, vcc
	s_waitcnt lgkmcnt(3)
	v_cndmask_b32_e64 v16, v8, v22, s[4:5]
	v_cndmask_b32_e64 v13, v38, 0, vcc
	v_cndmask_b32_e64 v15, v36, 0, vcc
	s_waitcnt lgkmcnt(2)
	v_cndmask_b32_e64 v17, v9, v23, s[4:5]
	v_lshlrev_b32_e32 v8, 16, v16
	v_and_b32_e32 v9, 0xffff0000, v16
	v_cndmask_b32_e64 v15, v26, v15, s[6:7]
	v_cndmask_b32_e64 v19, v28, v13, s[6:7]
	v_cndmask_b32_e64 v21, v29, v12, s[6:7]
	v_pk_mul_f32 v[8:9], v[92:93], v[8:9]
	v_lshlrev_b32_e32 v12, 16, v32
	v_and_b32_e32 v13, 0xffff0000, v32
	s_waitcnt lgkmcnt(1)
	v_cndmask_b32_e64 v18, v10, v24, s[4:5]
	s_waitcnt lgkmcnt(0)
	v_cndmask_b32_e64 v20, v11, v25, s[4:5]
	v_lshlrev_b32_e32 v10, 16, v15
	v_and_b32_e32 v11, 0xffff0000, v15
	v_pk_fma_f32 v[8:9], v[84:85], v[12:13], v[8:9]
	v_cndmask_b32_e64 v14, v37, 0, vcc
	v_pk_fma_f32 v[8:9], v[80:81], v[10:11], v[8:9]
	v_cndmask_b32_e64 v14, v27, v14, s[6:7]
	v_pk_add_f32 v[8:9], v[88:89], v[8:9]
	v_lshlrev_b32_e32 v12, 16, v33
	v_mul_f32_e32 v10, 0xbfb8aa3b, v8
	v_mul_f32_e32 v11, 0xbfb8aa3b, v9
	v_exp_f32_e32 v10, v10
	v_exp_f32_e32 v11, v11
	v_and_b32_e32 v13, 0xffff0000, v33
	s_andn2_b64 vcc, exec, s[68:69]
	v_add_f32_e32 v10, 1.0, v10
	v_add_f32_e32 v11, 1.0, v11
	v_rcp_f32_e32 v10, v10
	v_rcp_f32_e32 v11, v11
	s_nop 0
	v_pk_mul_f32 v[8:9], v[8:9], v[10:11]
	s_nop 0
	v_pk_mul_f32 v[4:5], v[4:5], v[8:9]
	v_lshlrev_b32_e32 v8, 16, v17
	v_and_b32_e32 v9, 0xffff0000, v17
	v_pk_mul_f32 v[8:9], v[94:95], v[8:9]
	v_lshlrev_b32_e32 v10, 16, v14
	v_and_b32_e32 v11, 0xffff0000, v14
	v_pk_fma_f32 v[8:9], v[86:87], v[12:13], v[8:9]
	v_lshlrev_b32_e32 v12, 16, v34
	v_pk_fma_f32 v[8:9], v[82:83], v[10:11], v[8:9]
	v_and_b32_e32 v13, 0xffff0000, v34
	v_pk_add_f32 v[8:9], v[90:91], v[8:9]
	s_nop 0
	v_mul_f32_e32 v10, 0xbfb8aa3b, v8
	v_mul_f32_e32 v11, 0xbfb8aa3b, v9
	v_exp_f32_e32 v10, v10
	v_exp_f32_e32 v11, v11
	v_add_f32_e32 v10, 1.0, v10
	v_add_f32_e32 v11, 1.0, v11
	v_rcp_f32_e32 v10, v10
	v_rcp_f32_e32 v11, v11
	s_nop 0
	v_pk_mul_f32 v[8:9], v[8:9], v[10:11]
	s_nop 0
	v_pk_mul_f32 v[6:7], v[6:7], v[8:9]
	v_lshlrev_b32_e32 v8, 16, v18
	v_and_b32_e32 v9, 0xffff0000, v18
	v_pk_mul_f32 v[8:9], v[76:77], v[8:9]
	v_lshlrev_b32_e32 v10, 16, v19
	v_and_b32_e32 v11, 0xffff0000, v19
	v_pk_fma_f32 v[8:9], v[68:69], v[12:13], v[8:9]
	v_lshlrev_b32_e32 v12, 16, v35
	v_pk_fma_f32 v[8:9], v[64:65], v[10:11], v[8:9]
	v_and_b32_e32 v13, 0xffff0000, v35
	v_pk_add_f32 v[8:9], v[72:73], v[8:9]
	s_nop 0
	v_mul_f32_e32 v10, 0xbfb8aa3b, v8
	v_mul_f32_e32 v11, 0xbfb8aa3b, v9
	v_exp_f32_e32 v10, v10
	v_exp_f32_e32 v11, v11
	v_add_f32_e32 v10, 1.0, v10
	v_add_f32_e32 v11, 1.0, v11
	v_rcp_f32_e32 v10, v10
	v_rcp_f32_e32 v11, v11
	s_nop 0
	v_pk_mul_f32 v[8:9], v[8:9], v[10:11]
	s_nop 0
	v_pk_mul_f32 v[8:9], v[0:1], v[8:9]
	v_lshlrev_b32_e32 v0, 16, v20
	v_and_b32_e32 v1, 0xffff0000, v20
	v_pk_mul_f32 v[0:1], v[78:79], v[0:1]
	v_lshlrev_b32_e32 v10, 16, v21
	v_and_b32_e32 v11, 0xffff0000, v21
	v_pk_fma_f32 v[0:1], v[70:71], v[12:13], v[0:1]
	s_nop 0
	v_pk_fma_f32 v[0:1], v[66:67], v[10:11], v[0:1]
	s_nop 0
	v_pk_add_f32 v[0:1], v[74:75], v[0:1]
	s_nop 0
	v_mul_f32_e32 v10, 0xbfb8aa3b, v0
	v_mul_f32_e32 v11, 0xbfb8aa3b, v1
	v_exp_f32_e32 v10, v10
	v_exp_f32_e32 v11, v11
	v_add_f32_e32 v10, 1.0, v10
	v_add_f32_e32 v11, 1.0, v11
	v_rcp_f32_e32 v10, v10
	v_rcp_f32_e32 v11, v11
	s_nop 0
	v_pk_mul_f32 v[0:1], v[0:1], v[10:11]
	s_nop 0
	v_pk_mul_f32 v[10:11], v[2:3], v[0:1]
	v_cvt_pk_bf16_f32 v0, v4, v5
	v_cvt_pk_bf16_f32 v1, v6, v7
	v_cvt_pk_bf16_f32 v2, v8, v9
	v_cvt_pk_bf16_f32 v3, v10, v11
	global_store_dwordx4 v[112:113], v[0:3], off offset:256
	s_cbranch_vccnz .LBB0_1053
	s_andn2_b64 vcc, exec, s[36:37]
	s_cbranch_vccnz .LBB0_1052
	s_barrier
	s_branch .LBB0_1052
